# non-temporal hint on P0's read-once f32 weight/activation loads and on P8's final output stores
# speedup vs baseline: 1.0123x; 1.0123x over previous
; template <int MODE  >
; __device__ __forceinline__ void transpose_item(const float* W, int K, int N, bf16_t* WT, int ldt, int koff, const float* ks, float* scr, int item, int lane) {
;     const int nblk = (N + 31) / 32, kb = item / nblk, nb = item % nblk, k0 = 64 * kb, n0 = 32 * nb;
;     const int nn = n0 + (lane & 31);
;     float v[32]; const float* wp = W + (size_t)(k0 + (lane >> 5)) * N + nn; const bool nok = nn < N;
; #pragma unroll
;     for (int i = 0; i < 32; ++i) v[i] = nok ? wp[(size_t)(2 * i) * N] : 0.f;
; #pragma unroll
;     for (int i = 0; i < 32; ++i) { const int kk = 2 * i + (lane >> 5); float x = v[i]; if (MODE != 0) x *= ks[k0 + kk]; scr[kk * 33 + (lane & 31)] = x; }
; __device__ __forceinline__ void phase0(const Args& a, unsigned char* lds, int tid) {
;     ...
;     for (int it = gw; it < NIT; it += NGW) {
;         int r = it;
;         if (r < I_IN) { transpose_item<1>(a.w_in, DM, DIN, WIN, DM, 0, a.norm1, scr, r, lane); continue; } r -= I_IN;
;         if (r < I_PS) { transpose_item<0>(a.p_swa, 1024, DM, PCAT, OC, 0, nullptr, scr, r, lane); continue; } r -= I_PS;
;         if (r < I_PG) { transpose_item<0>(a.p_gla, DM, DM, PCAT, OC, 1024, nullptr, scr, r, lane); continue; } r -= I_PG;
;         if (r < I_WO) { transpose_item<0>(a.w_o, DM, DM, WO, DM, 0, nullptr, scr, r, lane); continue; } r -= I_WO;
;         if (r < I_UP) { transpose_item<2>(a.w_up, DM, DFF, WUP, DM, 0, a.norm2, scr, r, lane); continue; } r -= I_UP;
;         transpose_item<0>(a.w_down, DFF, DM, WDN, DFF, 0, nullptr, scr, r, lane);
.LBB0_12:
	v_cmp_lt_i32_e32 vcc, s24, v64
	s_and_saveexec_b64 s[4:5], vcc
	s_xor_b64 s[4:5], exec, s[4:5]
	s_cbranch_execz .LBB0_30
	v_cmp_lt_u32_e32 vcc, s25, v64
	s_and_saveexec_b64 s[16:17], vcc
	s_xor_b64 s[16:17], exec, s[16:17]
	s_cbranch_execz .LBB0_27
	v_cmp_lt_u32_e32 vcc, s26, v64
	s_and_saveexec_b64 s[18:19], vcc
	s_xor_b64 s[18:19], exec, s[18:19]
	s_cbranch_execz .LBB0_24
	v_cmp_lt_u32_e32 vcc, s27, v64
	s_and_saveexec_b64 s[20:21], vcc
	s_xor_b64 s[20:21], exec, s[20:21]
	s_cbranch_execz .LBB0_21
	v_cmp_lt_u32_e32 vcc, s28, v64
	s_and_saveexec_b64 s[22:23], vcc
	s_xor_b64 s[22:23], exec, s[22:23]
	s_cbranch_execz .LBB0_18
	v_add_u32_e32 v2, 0xffff9de0, v64
	v_and_b32_e32 v65, 0x1fc0, v2
	v_add_u32_e32 v2, 0xfff3bc00, v63
	v_and_b32_e32 v76, 0x7e0, v2
	v_or_b32_e32 v2, v65, v6
	v_or_b32_e32 v4, v76, v1
	v_lshlrev_b32_e32 v8, 13, v2
	v_lshl_add_u64 v[2:3], s[80:81], 0, v[8:9]
	v_lshlrev_b32_e32 v8, 2, v4
	v_lshl_add_u64 v[2:3], v[2:3], 0, v[8:9]
	v_add_co_u32_e32 v4, vcc, 0x4000, v2
	s_nop 1
	v_addc_co_u32_e32 v5, vcc, 0, v3, vcc
	v_add_co_u32_e32 v22, vcc, 0x8000, v2
	s_nop 1
	v_addc_co_u32_e32 v23, vcc, 0, v3, vcc
	v_add_co_u32_e32 v24, vcc, 0xc000, v2
	s_nop 1
	v_addc_co_u32_e32 v25, vcc, 0, v3, vcc
	v_add_co_u32_e32 v66, vcc, 0x10000, v2
	s_nop 1
	v_addc_co_u32_e32 v67, vcc, 0, v3, vcc
	v_add_co_u32_e32 v68, vcc, 0x14000, v2
	s_nop 1
	v_addc_co_u32_e32 v69, vcc, 0, v3, vcc
	v_add_co_u32_e32 v70, vcc, 0x18000, v2
	s_nop 1
	v_addc_co_u32_e32 v71, vcc, 0, v3, vcc
	v_add_co_u32_e32 v72, vcc, 0x1c000, v2
	s_nop 1
	v_addc_co_u32_e32 v73, vcc, 0, v3, vcc
	global_load_dword v8, v[2:3], off nt
	global_load_dword v77, v[4:5], off nt
	global_load_dword v78, v[22:23], off nt
	global_load_dword v79, v[24:25], off nt
	global_load_dword v80, v[66:67], off nt
	global_load_dword v81, v[68:69], off nt
	global_load_dword v82, v[70:71], off nt
	global_load_dword v83, v[72:73], off nt
	v_add_co_u32_e32 v4, vcc, 0x20000, v2
	s_nop 1
	v_addc_co_u32_e32 v5, vcc, 0, v3, vcc
	v_add_co_u32_e32 v22, vcc, 0x24000, v2
	s_nop 1
	v_addc_co_u32_e32 v23, vcc, 0, v3, vcc
	v_add_co_u32_e32 v24, vcc, 0x28000, v2
	s_nop 1
	v_addc_co_u32_e32 v25, vcc, 0, v3, vcc
	v_add_co_u32_e32 v66, vcc, 0x2c000, v2
	s_nop 1
	v_addc_co_u32_e32 v67, vcc, 0, v3, vcc
	v_add_co_u32_e32 v68, vcc, 0x30000, v2
	s_nop 1
	v_addc_co_u32_e32 v69, vcc, 0, v3, vcc
	v_add_co_u32_e32 v70, vcc, 0x34000, v2
	s_nop 1
	v_addc_co_u32_e32 v71, vcc, 0, v3, vcc
	v_add_co_u32_e32 v72, vcc, 0x38000, v2
	s_nop 1
	v_addc_co_u32_e32 v73, vcc, 0, v3, vcc
	v_add_co_u32_e32 v74, vcc, 0x3c000, v2
	s_nop 1
	v_addc_co_u32_e32 v75, vcc, 0, v3, vcc
	global_load_dword v84, v[4:5], off nt
	global_load_dword v85, v[22:23], off nt
	global_load_dword v86, v[24:25], off nt
	global_load_dword v87, v[66:67], off nt
	global_load_dword v88, v[68:69], off nt
	global_load_dword v89, v[70:71], off nt
	global_load_dword v90, v[72:73], off nt
	global_load_dword v91, v[74:75], off nt
	v_add_co_u32_e32 v4, vcc, 0x40000, v2
	s_nop 1
	v_addc_co_u32_e32 v5, vcc, 0, v3, vcc
	v_add_co_u32_e32 v22, vcc, 0x44000, v2
	s_nop 1
	v_addc_co_u32_e32 v23, vcc, 0, v3, vcc
	v_add_co_u32_e32 v24, vcc, 0x48000, v2
	s_nop 1
	v_addc_co_u32_e32 v25, vcc, 0, v3, vcc
	v_add_co_u32_e32 v66, vcc, 0x4c000, v2
	s_nop 1
	v_addc_co_u32_e32 v67, vcc, 0, v3, vcc
	v_add_co_u32_e32 v68, vcc, 0x50000, v2
	s_nop 1
	v_addc_co_u32_e32 v69, vcc, 0, v3, vcc
	v_add_co_u32_e32 v70, vcc, 0x54000, v2
	s_nop 1
	v_addc_co_u32_e32 v71, vcc, 0, v3, vcc
	v_add_co_u32_e32 v72, vcc, 0x58000, v2
	s_nop 1
	v_addc_co_u32_e32 v73, vcc, 0, v3, vcc
	v_add_co_u32_e32 v74, vcc, 0x5c000, v2
	s_nop 1
	v_addc_co_u32_e32 v75, vcc, 0, v3, vcc
	global_load_dword v92, v[4:5], off nt
	global_load_dword v93, v[22:23], off nt
	global_load_dword v94, v[24:25], off nt
	global_load_dword v95, v[66:67], off nt
	global_load_dword v96, v[68:69], off nt
	global_load_dword v97, v[70:71], off nt
	global_load_dword v98, v[72:73], off nt
	s_nop 0
	global_load_dword v74, v[74:75], off nt
	v_add_co_u32_e32 v4, vcc, 0x60000, v2
	s_nop 1
	v_addc_co_u32_e32 v5, vcc, 0, v3, vcc
	v_add_co_u32_e32 v22, vcc, 0x64000, v2
	s_nop 1
	v_addc_co_u32_e32 v23, vcc, 0, v3, vcc
	v_add_co_u32_e32 v24, vcc, 0x68000, v2
	s_nop 1
	v_addc_co_u32_e32 v25, vcc, 0, v3, vcc
	v_add_co_u32_e32 v66, vcc, 0x6c000, v2
	s_nop 1
	v_addc_co_u32_e32 v67, vcc, 0, v3, vcc
	v_add_co_u32_e32 v68, vcc, 0x70000, v2
	s_nop 1
	v_addc_co_u32_e32 v69, vcc, 0, v3, vcc
	v_add_co_u32_e32 v70, vcc, 0x74000, v2
	s_nop 1
	v_addc_co_u32_e32 v71, vcc, 0, v3, vcc
	v_add_co_u32_e32 v72, vcc, 0x78000, v2
	s_nop 1
	v_addc_co_u32_e32 v73, vcc, 0, v3, vcc
	v_add_co_u32_e32 v2, vcc, 0x7c000, v2
	s_nop 1
	v_addc_co_u32_e32 v3, vcc, 0, v3, vcc
	global_load_dword v4, v[4:5], off nt
	s_nop 0
	global_load_dword v5, v[22:23], off nt
	s_nop 0
	global_load_dword v22, v[24:25], off nt
	global_load_dword v23, v[66:67], off nt
	s_nop 0
	global_load_dword v24, v[68:69], off nt
	global_load_dword v25, v[70:71], off nt
	global_load_dword v66, v[72:73], off nt
	s_nop 0
	global_load_dword v2, v[2:3], off nt
	v_add_u32_e32 v3, 0x400, v26
	s_waitcnt vmcnt(30)
	ds_write2_b32 v26, v8, v77 offset1:66
	s_waitcnt vmcnt(28)
	ds_write2_b32 v26, v78, v79 offset0:132 offset1:198
	s_waitcnt vmcnt(26)
	ds_write2_b32 v3, v80, v81 offset0:8 offset1:74
	s_waitcnt vmcnt(24)
	ds_write2_b32 v3, v82, v83 offset0:140 offset1:206
	v_add_u32_e32 v3, 0x800, v26
	s_waitcnt vmcnt(22)
	ds_write2_b32 v3, v84, v85 offset0:16 offset1:82
	s_waitcnt vmcnt(20)
	ds_write2_b32 v3, v86, v87 offset0:148 offset1:214
	v_add_u32_e32 v3, 0xc00, v26
	s_waitcnt vmcnt(18)
	ds_write2_b32 v3, v88, v89 offset0:24 offset1:90
	s_waitcnt vmcnt(16)
; __device__ __forceinline__ unsigned cvt_pk_bf16(float lo, float hi) { unsigned r; asm volatile("v_cvt_pk_bf16_f32 %0, %1, %2" : "=v"(r) : "v"(lo), "v"(hi)); return r; }
; #define LDS_WAIT() asm volatile("s_waitcnt lgkmcnt(0)" ::: "memory")
; template <int MODE  >
; __device__ __forceinline__ void transpose_item(const float* W, int K, int N, bf16_t* WT, int ldt, int koff, const float* ks, float* scr, int item, int lane) {
;     const int nblk = (N + 31) / 32, kb = item / nblk, nb = item % nblk, k0 = 64 * kb, n0 = 32 * nb;
;     const int nn = n0 + (lane & 31);
;     float v[32]; const float* wp = W + (size_t)(k0 + (lane >> 5)) * N + nn; const bool nok = nn < N;
; #pragma unroll
;     for (int i = 0; i < 32; ++i) v[i] = nok ? wp[(size_t)(2 * i) * N] : 0.f;
;     ...
;     for (int i = 0; i < 32; ++i) { const int kk = 2 * i + (lane >> 5); float x = v[i]; if (MODE != 0) x *= ks[k0 + kk]; scr[kk * 33 + (lane & 31)] = x; }
;     LDS_WAIT(); asm volatile("" ::: "memory");
;     const int c = lane & 7;
; #pragma unroll
;     for (int j = 0; j < 4; ++j) { const int nl = (lane >> 3) + 8 * j, n = n0 + nl; const float* s = scr + (8 * c) * 33 + nl;
;         u32x4 o; o.x = cvt_pk_bf16(s[0 * 33], s[1 * 33]); o.y = cvt_pk_bf16(s[2 * 33], s[3 * 33]); o.z = cvt_pk_bf16(s[4 * 33], s[5 * 33]); o.w = cvt_pk_bf16(s[6 * 33], s[7 * 33]);
;         int dst = n; if (MODE == 1) dst = n < 7680 ? n : (n < 7696 ? ZAG + (n - 7680) : n - 16);
;         if (n < N) *(u32x4*)(WT + (size_t)dst * ldt + koff + k0 + 8 * c) = o; }
;     LDS_WAIT(); asm volatile("" ::: "memory");
	ds_write2_b32 v3, v90, v91 offset0:156 offset1:222
	v_add_u32_e32 v3, 0x1000, v26
	s_waitcnt vmcnt(14)
	ds_write2_b32 v3, v92, v93 offset0:32 offset1:98
	s_waitcnt vmcnt(12)
	ds_write2_b32 v3, v94, v95 offset0:164 offset1:230
	v_add_u32_e32 v3, 0x1400, v26
	s_waitcnt vmcnt(10)
	ds_write2_b32 v3, v96, v97 offset0:40 offset1:106
	s_waitcnt vmcnt(8)
	ds_write2_b32 v3, v98, v74 offset0:172 offset1:238
	v_add_u32_e32 v3, 0x1800, v26
	s_waitcnt vmcnt(6)
	ds_write2_b32 v3, v4, v5 offset0:48 offset1:114
	s_waitcnt vmcnt(4)
	ds_write2_b32 v3, v22, v23 offset0:180 offset1:246
	v_add_u32_e32 v3, 0x1c00, v26
	s_waitcnt vmcnt(2)
	ds_write2_b32 v3, v24, v25 offset0:56 offset1:122
	s_waitcnt vmcnt(0)
	ds_write2_b32 v3, v66, v2 offset0:188 offset1:254
	s_waitcnt lgkmcnt(0)
	ds_read2_b32 v[2:3], v28 offset1:33
	v_lshlrev_b32_e32 v8, 1, v65
	s_waitcnt lgkmcnt(0)
	v_cvt_pk_bf16_f32 v2, v2, v3
	ds_read2_b32 v[4:5], v28 offset0:66 offset1:99
	v_lshl_add_u64 v[24:25], v[10:11], 0, v[8:9]
	v_or_b32_e32 v8, v76, v27
	s_waitcnt lgkmcnt(0)
	v_cvt_pk_bf16_f32 v3, v4, v5
	ds_read2_b32 v[4:5], v28 offset0:132 offset1:165
	v_lshlrev_b32_e32 v8, 14, v8
	s_waitcnt lgkmcnt(0)
	v_cvt_pk_bf16_f32 v4, v4, v5
	ds_read2_b32 v[22:23], v28 offset0:198 offset1:231
	s_waitcnt lgkmcnt(0)
	v_cvt_pk_bf16_f32 v5, v22, v23
	v_lshl_add_u64 v[66:67], v[24:25], 0, v[8:9]
	ds_read2_b32 v[22:23], v28 offset0:8 offset1:41
	global_store_dwordx4 v[66:67], v[2:5], off
	v_or_b32_e32 v8, v76, v29
	v_lshlrev_b32_e32 v8, 14, v8
	s_waitcnt lgkmcnt(0)
	v_cvt_pk_bf16_f32 v2, v22, v23
	ds_read2_b32 v[4:5], v28 offset0:74 offset1:107
	s_waitcnt lgkmcnt(0)
	v_cvt_pk_bf16_f32 v3, v4, v5
	ds_read2_b32 v[4:5], v28 offset0:140 offset1:173
	s_waitcnt lgkmcnt(0)
	v_cvt_pk_bf16_f32 v4, v4, v5
	ds_read2_b32 v[22:23], v28 offset0:206 offset1:239
	s_waitcnt lgkmcnt(0)
	v_cvt_pk_bf16_f32 v5, v22, v23
	v_lshl_add_u64 v[66:67], v[24:25], 0, v[8:9]
	ds_read2_b32 v[22:23], v28 offset0:16 offset1:49
	global_store_dwordx4 v[66:67], v[2:5], off
	v_or_b32_e32 v8, v76, v30
	v_lshlrev_b32_e32 v8, 14, v8
	s_waitcnt lgkmcnt(0)
	v_cvt_pk_bf16_f32 v2, v22, v23
	ds_read2_b32 v[4:5], v28 offset0:82 offset1:115
	s_waitcnt lgkmcnt(0)
	v_cvt_pk_bf16_f32 v3, v4, v5
	ds_read2_b32 v[4:5], v28 offset0:148 offset1:181
	s_waitcnt lgkmcnt(0)
	v_cvt_pk_bf16_f32 v4, v4, v5
	ds_read2_b32 v[22:23], v28 offset0:214 offset1:247
	s_waitcnt lgkmcnt(0)
	v_cvt_pk_bf16_f32 v5, v22, v23
	v_lshl_add_u64 v[66:67], v[24:25], 0, v[8:9]
	ds_read2_b32 v[22:23], v28 offset0:24 offset1:57
	global_store_dwordx4 v[66:67], v[2:5], off
	v_or_b32_e32 v8, v76, v31
	v_lshlrev_b32_e32 v8, 14, v8
	s_waitcnt lgkmcnt(0)
	v_cvt_pk_bf16_f32 v2, v22, v23
	ds_read2_b32 v[4:5], v28 offset0:90 offset1:123
	s_waitcnt lgkmcnt(0)
	v_cvt_pk_bf16_f32 v3, v4, v5
	ds_read2_b32 v[4:5], v28 offset0:156 offset1:189
	s_waitcnt lgkmcnt(0)
	v_cvt_pk_bf16_f32 v4, v4, v5
	ds_read2_b32 v[22:23], v28 offset0:222 offset1:255
	s_waitcnt lgkmcnt(0)
	v_cvt_pk_bf16_f32 v5, v22, v23
	v_lshl_add_u64 v[22:23], v[24:25], 0, v[8:9]
	global_store_dwordx4 v[22:23], v[2:5], off
	s_waitcnt lgkmcnt(0)
.LBB0_18:
	s_andn2_saveexec_b64 s[22:23], s[22:23]
	s_cbranch_execz .LBB0_20
	v_add_u32_e32 v2, 0xffffbde0, v64
	v_lshrrev_b32_e32 v2, 2, v2
	v_and_b32_e32 v3, 0x7c0, v2
	v_add_u32_e32 v2, 0xfff7bc00, v63
	v_and_b32_e32 v2, 0x1fe0, v2
	v_or_b32_e32 v24, v3, v6
	v_readlane_b32 s40, v249, 5
	v_or_b32_e32 v22, v2, v1
	v_lshlrev_b32_e32 v8, 15, v24
	v_readlane_b32 s54, v249, 19
	v_readlane_b32 s55, v249, 20
	v_readlane_b32 s52, v249, 17
	v_readlane_b32 s53, v249, 18
	v_lshl_add_u64 v[4:5], s[54:55], 0, v[8:9]
	v_lshlrev_b32_e32 v8, 2, v22
	v_lshl_add_u64 v[4:5], v[4:5], 0, v[8:9]
	v_add_co_u32_e32 v22, vcc, 0x10000, v4
	global_load_dword v8, v[4:5], off nt
	s_nop 0
	v_addc_co_u32_e32 v23, vcc, 0, v5, vcc
	global_load_dword v25, v[22:23], off nt
	v_add_co_u32_e32 v22, vcc, 0x20000, v4
	v_readlane_b32 s41, v249, 6
	s_nop 0
	v_addc_co_u32_e32 v23, vcc, 0, v5, vcc
	global_load_dword v65, v[22:23], off nt
	v_add_co_u32_e32 v22, vcc, 0x30000, v4
	v_readlane_b32 s42, v249, 7
	s_nop 0
	v_addc_co_u32_e32 v23, vcc, 0, v5, vcc
	global_load_dword v66, v[22:23], off nt
	v_add_co_u32_e32 v22, vcc, 0x40000, v4
	v_readlane_b32 s43, v249, 8
	s_nop 0
	v_addc_co_u32_e32 v23, vcc, 0, v5, vcc
	global_load_dword v67, v[22:23], off nt
	v_add_co_u32_e32 v22, vcc, 0x50000, v4
	v_readlane_b32 s44, v249, 9
	s_nop 0
	v_addc_co_u32_e32 v23, vcc, 0, v5, vcc
	global_load_dword v68, v[22:23], off nt
	v_add_co_u32_e32 v22, vcc, 0x60000, v4
	v_readlane_b32 s45, v249, 10
	s_nop 0
	v_addc_co_u32_e32 v23, vcc, 0, v5, vcc
	global_load_dword v69, v[22:23], off nt
	v_add_co_u32_e32 v22, vcc, 0x70000, v4
	v_readlane_b32 s46, v249, 11
	s_nop 0
	v_addc_co_u32_e32 v23, vcc, 0, v5, vcc
	global_load_dword v70, v[22:23], off nt
	v_add_co_u32_e32 v22, vcc, 0x80000, v4
	v_readlane_b32 s47, v249, 12
	s_nop 0
	v_addc_co_u32_e32 v23, vcc, 0, v5, vcc
	global_load_dword v71, v[22:23], off nt
	v_add_co_u32_e32 v22, vcc, 0x90000, v4
	v_readlane_b32 s48, v249, 13
	s_nop 0
	v_addc_co_u32_e32 v23, vcc, 0, v5, vcc
	global_load_dword v72, v[22:23], off nt
	v_add_co_u32_e32 v22, vcc, 0xa0000, v4
	v_readlane_b32 s49, v249, 14
	s_nop 0
	v_addc_co_u32_e32 v23, vcc, 0, v5, vcc
	global_load_dword v73, v[22:23], off nt
	v_add_co_u32_e32 v22, vcc, 0xb0000, v4
	v_readlane_b32 s50, v249, 15
	s_nop 0
	v_addc_co_u32_e32 v23, vcc, 0, v5, vcc
	global_load_dword v74, v[22:23], off nt
	v_add_co_u32_e32 v22, vcc, 0xc0000, v4
	v_readlane_b32 s51, v249, 16
	s_nop 0
	v_addc_co_u32_e32 v23, vcc, 0, v5, vcc
	global_load_dword v75, v[22:23], off nt
	v_add_co_u32_e32 v22, vcc, 0xd0000, v4
; template <int MODE  >
; __device__ __forceinline__ void transpose_item(const float* W, int K, int N, bf16_t* WT, int ldt, int koff, const float* ks, float* scr, int item, int lane) {
;     ...
;     float v[32]; const float* wp = W + (size_t)(k0 + (lane >> 5)) * N + nn; const bool nok = nn < N;
; #pragma unroll
;     for (int i = 0; i < 32; ++i) v[i] = nok ? wp[(size_t)(2 * i) * N] : 0.f;
; #pragma unroll
;     for (int i = 0; i < 32; ++i) { const int kk = 2 * i + (lane >> 5); float x = v[i]; if (MODE != 0) x *= ks[k0 + kk]; scr[kk * 33 + (lane & 31)] = x; }
	s_nop 1
	v_addc_co_u32_e32 v23, vcc, 0, v5, vcc
	global_load_dword v76, v[22:23], off nt
	v_add_co_u32_e32 v22, vcc, 0xe0000, v4
	s_nop 1
	v_addc_co_u32_e32 v23, vcc, 0, v5, vcc
	global_load_dword v77, v[22:23], off nt
	v_add_co_u32_e32 v22, vcc, 0xf0000, v4
	s_nop 1
	v_addc_co_u32_e32 v23, vcc, 0, v5, vcc
	global_load_dword v78, v[22:23], off nt
	v_add_co_u32_e32 v22, vcc, 0x100000, v4
	s_nop 1
	v_addc_co_u32_e32 v23, vcc, 0, v5, vcc
	global_load_dword v79, v[22:23], off nt
	v_add_co_u32_e32 v22, vcc, 0x110000, v4
	s_nop 1
	v_addc_co_u32_e32 v23, vcc, 0, v5, vcc
	global_load_dword v80, v[22:23], off nt
	v_add_co_u32_e32 v22, vcc, 0x120000, v4
	s_nop 1
	v_addc_co_u32_e32 v23, vcc, 0, v5, vcc
	global_load_dword v81, v[22:23], off nt
	v_add_co_u32_e32 v22, vcc, 0x130000, v4
	s_nop 1
	v_addc_co_u32_e32 v23, vcc, 0, v5, vcc
	global_load_dword v82, v[22:23], off nt
	v_add_co_u32_e32 v22, vcc, 0x140000, v4
	s_nop 1
	v_addc_co_u32_e32 v23, vcc, 0, v5, vcc
	global_load_dword v83, v[22:23], off nt
	v_add_co_u32_e32 v22, vcc, 0x150000, v4
	s_nop 1
	v_addc_co_u32_e32 v23, vcc, 0, v5, vcc
	global_load_dword v84, v[22:23], off nt
	v_add_co_u32_e32 v22, vcc, 0x160000, v4
	s_nop 1
	v_addc_co_u32_e32 v23, vcc, 0, v5, vcc
	global_load_dword v85, v[22:23], off nt
	v_add_co_u32_e32 v22, vcc, 0x170000, v4
	s_nop 1
	v_addc_co_u32_e32 v23, vcc, 0, v5, vcc
	global_load_dword v86, v[22:23], off nt
	v_add_co_u32_e32 v22, vcc, 0x180000, v4
	s_nop 1
	v_addc_co_u32_e32 v23, vcc, 0, v5, vcc
	global_load_dword v87, v[22:23], off nt
	v_add_co_u32_e32 v22, vcc, 0x190000, v4
	s_nop 1
	v_addc_co_u32_e32 v23, vcc, 0, v5, vcc
	global_load_dword v88, v[22:23], off nt
	v_add_co_u32_e32 v22, vcc, 0x1a0000, v4
	s_nop 1
	v_addc_co_u32_e32 v23, vcc, 0, v5, vcc
	global_load_dword v89, v[22:23], off nt
	v_add_co_u32_e32 v22, vcc, 0x1b0000, v4
	s_nop 1
	v_addc_co_u32_e32 v23, vcc, 0, v5, vcc
	global_load_dword v90, v[22:23], off nt
	v_add_co_u32_e32 v22, vcc, 0x1c0000, v4
	s_nop 1
	v_addc_co_u32_e32 v23, vcc, 0, v5, vcc
	global_load_dword v91, v[22:23], off nt
	v_add_co_u32_e32 v22, vcc, 0x1d0000, v4
	s_nop 1
	v_addc_co_u32_e32 v23, vcc, 0, v5, vcc
	global_load_dword v92, v[22:23], off nt
	v_add_co_u32_e32 v22, vcc, 0x1e0000, v4
	s_nop 1
	v_addc_co_u32_e32 v23, vcc, 0, v5, vcc
	v_add_co_u32_e32 v4, vcc, 0x1f0000, v4
	global_load_dword v22, v[22:23], off nt
	s_nop 0
	v_addc_co_u32_e32 v5, vcc, 0, v5, vcc
	global_load_dword v4, v[4:5], off nt
	v_lshlrev_b32_e32 v5, 2, v24
	global_load_dword v23, v5, s[52:53] nt
	s_waitcnt vmcnt(0)
	v_mul_f32_e32 v8, v8, v23
	ds_write_b32 v26, v8
	global_load_dword v8, v5, s[52:53] offset:8 nt
	s_waitcnt vmcnt(0)
	v_mul_f32_e32 v8, v25, v8
	ds_write_b32 v32, v8
	global_load_dword v8, v5, s[52:53] offset:16 nt
	s_waitcnt vmcnt(0)
	v_mul_f32_e32 v8, v65, v8
	ds_write_b32 v33, v8
	global_load_dword v8, v5, s[52:53] offset:24 nt
	s_waitcnt vmcnt(0)
	v_mul_f32_e32 v8, v66, v8
	ds_write_b32 v34, v8
	global_load_dword v8, v5, s[52:53] offset:32 nt
	s_waitcnt vmcnt(0)
	v_mul_f32_e32 v8, v67, v8
	ds_write_b32 v35, v8
	global_load_dword v8, v5, s[52:53] offset:40 nt
	s_waitcnt vmcnt(0)
	v_mul_f32_e32 v8, v68, v8
	ds_write_b32 v36, v8
	global_load_dword v8, v5, s[52:53] offset:48 nt
	s_waitcnt vmcnt(0)
	v_mul_f32_e32 v8, v69, v8
	ds_write_b32 v37, v8
	global_load_dword v8, v5, s[52:53] offset:56 nt
	s_waitcnt vmcnt(0)
	v_mul_f32_e32 v8, v70, v8
	ds_write_b32 v38, v8
	global_load_dword v8, v5, s[52:53] offset:64 nt
	s_waitcnt vmcnt(0)
	v_mul_f32_e32 v8, v71, v8
	ds_write_b32 v39, v8
	global_load_dword v8, v5, s[52:53] offset:72 nt
	s_waitcnt vmcnt(0)
	v_mul_f32_e32 v8, v72, v8
	ds_write_b32 v40, v8
	global_load_dword v8, v5, s[52:53] offset:80 nt
	s_waitcnt vmcnt(0)
	v_mul_f32_e32 v8, v73, v8
	ds_write_b32 v41, v8
	global_load_dword v8, v5, s[52:53] offset:88 nt
	s_waitcnt vmcnt(0)
	v_mul_f32_e32 v8, v74, v8
	ds_write_b32 v42, v8
	global_load_dword v8, v5, s[52:53] offset:96 nt
	s_waitcnt vmcnt(0)
	v_mul_f32_e32 v8, v75, v8
	ds_write_b32 v43, v8
	global_load_dword v8, v5, s[52:53] offset:104 nt
	s_waitcnt vmcnt(0)
	v_mul_f32_e32 v8, v76, v8
	ds_write_b32 v44, v8
	global_load_dword v8, v5, s[52:53] offset:112 nt
	s_waitcnt vmcnt(0)
	v_mul_f32_e32 v8, v77, v8
	ds_write_b32 v45, v8
	global_load_dword v8, v5, s[52:53] offset:120 nt
	s_waitcnt vmcnt(0)
; __device__ __forceinline__ unsigned cvt_pk_bf16(float lo, float hi) { unsigned r; asm volatile("v_cvt_pk_bf16_f32 %0, %1, %2" : "=v"(r) : "v"(lo), "v"(hi)); return r; }
; #define LDS_WAIT() asm volatile("s_waitcnt lgkmcnt(0)" ::: "memory")
; template <int MODE  >
; __device__ __forceinline__ void transpose_item(const float* W, int K, int N, bf16_t* WT, int ldt, int koff, const float* ks, float* scr, int item, int lane) {
;     ...
;     for (int i = 0; i < 32; ++i) { const int kk = 2 * i + (lane >> 5); float x = v[i]; if (MODE != 0) x *= ks[k0 + kk]; scr[kk * 33 + (lane & 31)] = x; }
;     LDS_WAIT(); asm volatile("" ::: "memory");
;     const int c = lane & 7;
; #pragma unroll
;     for (int j = 0; j < 4; ++j) { const int nl = (lane >> 3) + 8 * j, n = n0 + nl; const float* s = scr + (8 * c) * 33 + nl;
;         u32x4 o; o.x = cvt_pk_bf16(s[0 * 33], s[1 * 33]); o.y = cvt_pk_bf16(s[2 * 33], s[3 * 33]); o.z = cvt_pk_bf16(s[4 * 33], s[5 * 33]); o.w = cvt_pk_bf16(s[6 * 33], s[7 * 33]);
;         int dst = n; if (MODE == 1) dst = n < 7680 ? n : (n < 7696 ? ZAG + (n - 7680) : n - 16);
;         if (n < N) *(u32x4*)(WT + (size_t)dst * ldt + koff + k0 + 8 * c) = o; }
	v_mul_f32_e32 v8, v78, v8
	ds_write_b32 v46, v8
	global_load_dword v8, v5, s[52:53] offset:128 nt
	s_waitcnt vmcnt(0)
	v_mul_f32_e32 v8, v79, v8
	ds_write_b32 v47, v8
	global_load_dword v8, v5, s[52:53] offset:136 nt
	s_waitcnt vmcnt(0)
	v_mul_f32_e32 v8, v80, v8
	ds_write_b32 v48, v8
	global_load_dword v8, v5, s[52:53] offset:144 nt
	s_waitcnt vmcnt(0)
	v_mul_f32_e32 v8, v81, v8
	ds_write_b32 v49, v8
	global_load_dword v8, v5, s[52:53] offset:152 nt
	s_waitcnt vmcnt(0)
	v_mul_f32_e32 v8, v82, v8
	ds_write_b32 v50, v8
	global_load_dword v8, v5, s[52:53] offset:160 nt
	s_waitcnt vmcnt(0)
	v_mul_f32_e32 v8, v83, v8
	ds_write_b32 v51, v8
	global_load_dword v8, v5, s[52:53] offset:168 nt
	s_waitcnt vmcnt(0)
	v_mul_f32_e32 v8, v84, v8
	ds_write_b32 v52, v8
	global_load_dword v8, v5, s[52:53] offset:176 nt
	s_waitcnt vmcnt(0)
	v_mul_f32_e32 v8, v85, v8
	ds_write_b32 v53, v8
	global_load_dword v8, v5, s[52:53] offset:184 nt
	s_waitcnt vmcnt(0)
	v_mul_f32_e32 v8, v86, v8
	ds_write_b32 v54, v8
	global_load_dword v8, v5, s[52:53] offset:192 nt
	s_waitcnt vmcnt(0)
	v_mul_f32_e32 v8, v87, v8
	ds_write_b32 v55, v8
	global_load_dword v8, v5, s[52:53] offset:200 nt
	s_waitcnt vmcnt(0)
	v_mul_f32_e32 v8, v88, v8
	ds_write_b32 v56, v8
	global_load_dword v8, v5, s[52:53] offset:208 nt
	s_waitcnt vmcnt(0)
	v_mul_f32_e32 v8, v89, v8
	ds_write_b32 v57, v8
	global_load_dword v8, v5, s[52:53] offset:216 nt
	s_waitcnt vmcnt(0)
	v_mul_f32_e32 v8, v90, v8
	ds_write_b32 v58, v8
	global_load_dword v8, v5, s[52:53] offset:224 nt
	s_waitcnt vmcnt(0)
	v_mul_f32_e32 v8, v91, v8
	ds_write_b32 v59, v8
	global_load_dword v8, v5, s[52:53] offset:232 nt
	s_waitcnt vmcnt(0)
	v_mul_f32_e32 v8, v92, v8
	ds_write_b32 v60, v8
	global_load_dword v8, v5, s[52:53] offset:240 nt
	s_waitcnt vmcnt(0)
	v_mul_f32_e32 v8, v22, v8
	global_load_dword v5, v5, s[52:53] offset:248 nt
	ds_write_b32 v61, v8
	v_lshlrev_b32_e32 v8, 1, v3
	v_or_b32_e32 v3, v2, v27
	s_waitcnt vmcnt(0)
	v_mul_f32_e32 v4, v4, v5
	ds_write_b32 v62, v4
	s_waitcnt lgkmcnt(0)
	ds_read2_b32 v[22:23], v28 offset1:33
	s_waitcnt lgkmcnt(0)
	v_cvt_pk_bf16_f32 v22, v22, v23
	ds_read2_b32 v[24:25], v28 offset0:66 offset1:99
	s_waitcnt lgkmcnt(0)
	v_cvt_pk_bf16_f32 v23, v24, v25
	ds_read2_b32 v[24:25], v28 offset0:132 offset1:165
	v_lshl_add_u64 v[4:5], v[12:13], 0, v[8:9]
	s_waitcnt lgkmcnt(0)
	v_cvt_pk_bf16_f32 v24, v24, v25
	ds_read2_b32 v[66:67], v28 offset0:198 offset1:231
	v_lshlrev_b32_e32 v8, 12, v3
	s_waitcnt lgkmcnt(0)
	v_cvt_pk_bf16_f32 v25, v66, v67
	v_lshl_add_u64 v[66:67], v[4:5], 0, v[8:9]
	global_store_dwordx4 v[66:67], v[22:25], off
	ds_read2_b32 v[22:23], v28 offset0:8 offset1:41
	v_or_b32_e32 v3, v2, v29
	s_waitcnt lgkmcnt(0)
	v_cvt_pk_bf16_f32 v22, v22, v23
	ds_read2_b32 v[24:25], v28 offset0:74 offset1:107
	s_waitcnt lgkmcnt(0)
	v_cvt_pk_bf16_f32 v23, v24, v25
	ds_read2_b32 v[24:25], v28 offset0:140 offset1:173
	s_waitcnt lgkmcnt(0)
	v_cvt_pk_bf16_f32 v24, v24, v25
	ds_read2_b32 v[66:67], v28 offset0:206 offset1:239
	v_lshlrev_b32_e32 v8, 12, v3
	s_waitcnt lgkmcnt(0)
	v_cvt_pk_bf16_f32 v25, v66, v67
	v_lshl_add_u64 v[66:67], v[4:5], 0, v[8:9]
	global_store_dwordx4 v[66:67], v[22:25], off
	ds_read2_b32 v[22:23], v28 offset0:16 offset1:49
	v_or_b32_e32 v3, v2, v30
	s_waitcnt lgkmcnt(0)
	v_cvt_pk_bf16_f32 v22, v22, v23
	ds_read2_b32 v[24:25], v28 offset0:82 offset1:115
	s_waitcnt lgkmcnt(0)
	v_cvt_pk_bf16_f32 v23, v24, v25
	ds_read2_b32 v[24:25], v28 offset0:148 offset1:181
	s_waitcnt lgkmcnt(0)
	v_cvt_pk_bf16_f32 v24, v24, v25
	ds_read2_b32 v[66:67], v28 offset0:214 offset1:247
	v_lshlrev_b32_e32 v8, 12, v3
	s_waitcnt lgkmcnt(0)
	v_cvt_pk_bf16_f32 v25, v66, v67
	v_lshl_add_u64 v[66:67], v[4:5], 0, v[8:9]
	global_store_dwordx4 v[66:67], v[22:25], off
	ds_read2_b32 v[22:23], v28 offset0:24 offset1:57
	v_or_b32_e32 v2, v2, v31
	s_waitcnt lgkmcnt(0)
	v_cvt_pk_bf16_f32 v22, v22, v23
	ds_read2_b32 v[24:25], v28 offset0:90 offset1:123
	v_lshlrev_b32_e32 v8, 12, v2
	s_waitcnt lgkmcnt(0)
	v_cvt_pk_bf16_f32 v23, v24, v25
	ds_read2_b32 v[24:25], v28 offset0:156 offset1:189
	v_lshl_add_u64 v[2:3], v[4:5], 0, v[8:9]
	s_waitcnt lgkmcnt(0)
	v_cvt_pk_bf16_f32 v24, v24, v25
	ds_read2_b32 v[66:67], v28 offset0:222 offset1:255
	s_waitcnt lgkmcnt(0)
	v_cvt_pk_bf16_f32 v25, v66, v67
	global_store_dwordx4 v[2:3], v[22:25], off
	s_waitcnt lgkmcnt(0)

; template <int MODE  >
; __device__ __forceinline__ void transpose_item(const float* W, int K, int N, bf16_t* WT, int ldt, int koff, const float* ks, float* scr, int item, int lane) {
;     ...
;     float v[32]; const float* wp = W + (size_t)(k0 + (lane >> 5)) * N + nn; const bool nok = nn < N;
; #pragma unroll
;     for (int i = 0; i < 32; ++i) v[i] = nok ? wp[(size_t)(2 * i) * N] : 0.f;
.LBB0_21:
	s_andn2_saveexec_b64 s[20:21], s[20:21]
	s_cbranch_execz .LBB0_23
	v_add_u32_e32 v2, 0xffffc5e0, v64
	v_and_b32_e32 v65, 0x1fc0, v2
	v_add_u32_e32 v2, 0xfff8bc00, v63
	v_and_b32_e32 v76, 0x7e0, v2
	v_or_b32_e32 v2, v65, v6
	v_readlane_b32 s40, v249, 5
	v_or_b32_e32 v4, v76, v1
	v_lshlrev_b32_e32 v8, 13, v2
	v_readlane_b32 s50, v249, 15
	v_readlane_b32 s51, v249, 16
	v_readlane_b32 s41, v249, 6
	v_readlane_b32 s42, v249, 7
	v_lshl_add_u64 v[2:3], s[50:51], 0, v[8:9]
	v_lshlrev_b32_e32 v8, 2, v4
	v_lshl_add_u64 v[2:3], v[2:3], 0, v[8:9]
	v_add_co_u32_e32 v4, vcc, 0x4000, v2
	v_readlane_b32 s43, v249, 8
	s_nop 0
	v_addc_co_u32_e32 v5, vcc, 0, v3, vcc
	v_add_co_u32_e32 v22, vcc, 0x8000, v2
	v_readlane_b32 s44, v249, 9
	s_nop 0
	v_addc_co_u32_e32 v23, vcc, 0, v3, vcc
	v_add_co_u32_e32 v24, vcc, 0xc000, v2
	v_readlane_b32 s45, v249, 10
	s_nop 0
	v_addc_co_u32_e32 v25, vcc, 0, v3, vcc
	v_add_co_u32_e32 v66, vcc, 0x10000, v2
	v_readlane_b32 s46, v249, 11
	s_nop 0
	v_addc_co_u32_e32 v67, vcc, 0, v3, vcc
	v_add_co_u32_e32 v68, vcc, 0x14000, v2
	v_readlane_b32 s47, v249, 12
	s_nop 0
	v_addc_co_u32_e32 v69, vcc, 0, v3, vcc
	v_add_co_u32_e32 v70, vcc, 0x18000, v2
	v_readlane_b32 s48, v249, 13
	s_nop 0
	v_addc_co_u32_e32 v71, vcc, 0, v3, vcc
	v_add_co_u32_e32 v72, vcc, 0x1c000, v2
	v_readlane_b32 s49, v249, 14
	s_nop 0
	v_addc_co_u32_e32 v73, vcc, 0, v3, vcc
	global_load_dword v8, v[2:3], off nt
	global_load_dword v77, v[4:5], off nt
	global_load_dword v78, v[22:23], off nt
	global_load_dword v79, v[24:25], off nt
	global_load_dword v80, v[66:67], off nt
	global_load_dword v81, v[68:69], off nt
	global_load_dword v82, v[70:71], off nt
	global_load_dword v83, v[72:73], off nt
	v_add_co_u32_e32 v4, vcc, 0x20000, v2
	v_readlane_b32 s52, v249, 17
	s_nop 0
	v_addc_co_u32_e32 v5, vcc, 0, v3, vcc
	v_add_co_u32_e32 v22, vcc, 0x24000, v2
	v_readlane_b32 s53, v249, 18
	s_nop 0
	v_addc_co_u32_e32 v23, vcc, 0, v3, vcc
	v_add_co_u32_e32 v24, vcc, 0x28000, v2
	v_readlane_b32 s54, v249, 19
	s_nop 0
	v_addc_co_u32_e32 v25, vcc, 0, v3, vcc
	v_add_co_u32_e32 v66, vcc, 0x2c000, v2
	v_readlane_b32 s55, v249, 20
	s_nop 0
	v_addc_co_u32_e32 v67, vcc, 0, v3, vcc
	v_add_co_u32_e32 v68, vcc, 0x30000, v2
	s_nop 1
	v_addc_co_u32_e32 v69, vcc, 0, v3, vcc
	v_add_co_u32_e32 v70, vcc, 0x34000, v2
	s_nop 1
	v_addc_co_u32_e32 v71, vcc, 0, v3, vcc
	v_add_co_u32_e32 v72, vcc, 0x38000, v2
	s_nop 1
	v_addc_co_u32_e32 v73, vcc, 0, v3, vcc
	v_add_co_u32_e32 v74, vcc, 0x3c000, v2
	s_nop 1
	v_addc_co_u32_e32 v75, vcc, 0, v3, vcc
	global_load_dword v84, v[4:5], off nt
	global_load_dword v85, v[22:23], off nt
	global_load_dword v86, v[24:25], off nt
	global_load_dword v87, v[66:67], off nt
	global_load_dword v88, v[68:69], off nt
	global_load_dword v89, v[70:71], off nt
	global_load_dword v90, v[72:73], off nt
	global_load_dword v91, v[74:75], off nt
	v_add_co_u32_e32 v4, vcc, 0x40000, v2
	s_nop 1
	v_addc_co_u32_e32 v5, vcc, 0, v3, vcc
	v_add_co_u32_e32 v22, vcc, 0x44000, v2
	s_nop 1
	v_addc_co_u32_e32 v23, vcc, 0, v3, vcc
	v_add_co_u32_e32 v24, vcc, 0x48000, v2
	s_nop 1
	v_addc_co_u32_e32 v25, vcc, 0, v3, vcc
	v_add_co_u32_e32 v66, vcc, 0x4c000, v2
	s_nop 1
	v_addc_co_u32_e32 v67, vcc, 0, v3, vcc
	v_add_co_u32_e32 v68, vcc, 0x50000, v2
	s_nop 1
	v_addc_co_u32_e32 v69, vcc, 0, v3, vcc
	v_add_co_u32_e32 v70, vcc, 0x54000, v2
	s_nop 1
	v_addc_co_u32_e32 v71, vcc, 0, v3, vcc
	v_add_co_u32_e32 v72, vcc, 0x58000, v2
	s_nop 1
	v_addc_co_u32_e32 v73, vcc, 0, v3, vcc
	v_add_co_u32_e32 v74, vcc, 0x5c000, v2
	s_nop 1
	v_addc_co_u32_e32 v75, vcc, 0, v3, vcc
	global_load_dword v92, v[4:5], off nt
	global_load_dword v93, v[22:23], off nt
	global_load_dword v94, v[24:25], off nt
	global_load_dword v95, v[66:67], off nt
	global_load_dword v96, v[68:69], off nt
	global_load_dword v97, v[70:71], off nt
	global_load_dword v98, v[72:73], off nt
	s_nop 0
	global_load_dword v74, v[74:75], off nt
	v_add_co_u32_e32 v4, vcc, 0x60000, v2
	s_nop 1
	v_addc_co_u32_e32 v5, vcc, 0, v3, vcc
	v_add_co_u32_e32 v22, vcc, 0x64000, v2
	s_nop 1
	v_addc_co_u32_e32 v23, vcc, 0, v3, vcc
	v_add_co_u32_e32 v24, vcc, 0x68000, v2
	s_nop 1
	v_addc_co_u32_e32 v25, vcc, 0, v3, vcc
	v_add_co_u32_e32 v66, vcc, 0x6c000, v2
	s_nop 1
	v_addc_co_u32_e32 v67, vcc, 0, v3, vcc
	v_add_co_u32_e32 v68, vcc, 0x70000, v2
	s_nop 1
	v_addc_co_u32_e32 v69, vcc, 0, v3, vcc
	v_add_co_u32_e32 v70, vcc, 0x74000, v2
	s_nop 1
	v_addc_co_u32_e32 v71, vcc, 0, v3, vcc
	v_add_co_u32_e32 v72, vcc, 0x78000, v2
	s_nop 1
	v_addc_co_u32_e32 v73, vcc, 0, v3, vcc
	v_add_co_u32_e32 v2, vcc, 0x7c000, v2
	s_nop 1
	v_addc_co_u32_e32 v3, vcc, 0, v3, vcc
	global_load_dword v4, v[4:5], off nt
	s_nop 0
	global_load_dword v5, v[22:23], off nt
	s_nop 0
	global_load_dword v22, v[24:25], off nt
	global_load_dword v23, v[66:67], off nt
	s_nop 0
	global_load_dword v24, v[68:69], off nt
	global_load_dword v25, v[70:71], off nt
	global_load_dword v66, v[72:73], off nt
	s_nop 0
	global_load_dword v2, v[2:3], off nt
	v_add_u32_e32 v3, 0x400, v26
	s_waitcnt vmcnt(30)
; __device__ __forceinline__ unsigned cvt_pk_bf16(float lo, float hi) { unsigned r; asm volatile("v_cvt_pk_bf16_f32 %0, %1, %2" : "=v"(r) : "v"(lo), "v"(hi)); return r; }
; #define LDS_WAIT() asm volatile("s_waitcnt lgkmcnt(0)" ::: "memory")
; template <int MODE  >
; __device__ __forceinline__ void transpose_item(const float* W, int K, int N, bf16_t* WT, int ldt, int koff, const float* ks, float* scr, int item, int lane) {
;     ...
;     for (int i = 0; i < 32; ++i) { const int kk = 2 * i + (lane >> 5); float x = v[i]; if (MODE != 0) x *= ks[k0 + kk]; scr[kk * 33 + (lane & 31)] = x; }
;     LDS_WAIT(); asm volatile("" ::: "memory");
;     const int c = lane & 7;
; #pragma unroll
;     for (int j = 0; j < 4; ++j) { const int nl = (lane >> 3) + 8 * j, n = n0 + nl; const float* s = scr + (8 * c) * 33 + nl;
;         u32x4 o; o.x = cvt_pk_bf16(s[0 * 33], s[1 * 33]); o.y = cvt_pk_bf16(s[2 * 33], s[3 * 33]); o.z = cvt_pk_bf16(s[4 * 33], s[5 * 33]); o.w = cvt_pk_bf16(s[6 * 33], s[7 * 33]);
;         int dst = n; if (MODE == 1) dst = n < 7680 ? n : (n < 7696 ? ZAG + (n - 7680) : n - 16);
;         if (n < N) *(u32x4*)(WT + (size_t)dst * ldt + koff + k0 + 8 * c) = o; }
	ds_write2_b32 v26, v8, v77 offset1:66
	s_waitcnt vmcnt(28)
	ds_write2_b32 v26, v78, v79 offset0:132 offset1:198
	s_waitcnt vmcnt(26)
	ds_write2_b32 v3, v80, v81 offset0:8 offset1:74
	s_waitcnt vmcnt(24)
	ds_write2_b32 v3, v82, v83 offset0:140 offset1:206
	v_add_u32_e32 v3, 0x800, v26
	s_waitcnt vmcnt(22)
	ds_write2_b32 v3, v84, v85 offset0:16 offset1:82
	s_waitcnt vmcnt(20)
	ds_write2_b32 v3, v86, v87 offset0:148 offset1:214
	v_add_u32_e32 v3, 0xc00, v26
	s_waitcnt vmcnt(18)
	ds_write2_b32 v3, v88, v89 offset0:24 offset1:90
	s_waitcnt vmcnt(16)
	ds_write2_b32 v3, v90, v91 offset0:156 offset1:222
	v_add_u32_e32 v3, 0x1000, v26
	s_waitcnt vmcnt(14)
	ds_write2_b32 v3, v92, v93 offset0:32 offset1:98
	s_waitcnt vmcnt(12)
	ds_write2_b32 v3, v94, v95 offset0:164 offset1:230
	v_add_u32_e32 v3, 0x1400, v26
	s_waitcnt vmcnt(10)
	ds_write2_b32 v3, v96, v97 offset0:40 offset1:106
	s_waitcnt vmcnt(8)
	ds_write2_b32 v3, v98, v74 offset0:172 offset1:238
	v_add_u32_e32 v3, 0x1800, v26
	s_waitcnt vmcnt(6)
	ds_write2_b32 v3, v4, v5 offset0:48 offset1:114
	s_waitcnt vmcnt(4)
	ds_write2_b32 v3, v22, v23 offset0:180 offset1:246
	v_add_u32_e32 v3, 0x1c00, v26
	s_waitcnt vmcnt(2)
	ds_write2_b32 v3, v24, v25 offset0:56 offset1:122
	s_waitcnt vmcnt(0)
	ds_write2_b32 v3, v66, v2 offset0:188 offset1:254
	s_waitcnt lgkmcnt(0)
	ds_read2_b32 v[2:3], v28 offset1:33
	v_lshlrev_b32_e32 v8, 1, v65
	s_waitcnt lgkmcnt(0)
	v_cvt_pk_bf16_f32 v2, v2, v3
	ds_read2_b32 v[4:5], v28 offset0:66 offset1:99
	v_lshl_add_u64 v[24:25], v[14:15], 0, v[8:9]
	v_or_b32_e32 v8, v76, v27
	s_waitcnt lgkmcnt(0)
	v_cvt_pk_bf16_f32 v3, v4, v5
	ds_read2_b32 v[4:5], v28 offset0:132 offset1:165
	v_lshlrev_b32_e32 v8, 12, v8
	s_waitcnt lgkmcnt(0)
	v_cvt_pk_bf16_f32 v4, v4, v5
	ds_read2_b32 v[22:23], v28 offset0:198 offset1:231
	s_waitcnt lgkmcnt(0)
	v_cvt_pk_bf16_f32 v5, v22, v23
	v_lshl_add_u64 v[66:67], v[24:25], 0, v[8:9]
	ds_read2_b32 v[22:23], v28 offset0:8 offset1:41
	global_store_dwordx4 v[66:67], v[2:5], off
	v_or_b32_e32 v8, v76, v29
	v_lshlrev_b32_e32 v8, 12, v8
	s_waitcnt lgkmcnt(0)
	v_cvt_pk_bf16_f32 v2, v22, v23
	ds_read2_b32 v[4:5], v28 offset0:74 offset1:107
	s_waitcnt lgkmcnt(0)
	v_cvt_pk_bf16_f32 v3, v4, v5
	ds_read2_b32 v[4:5], v28 offset0:140 offset1:173
	s_waitcnt lgkmcnt(0)
	v_cvt_pk_bf16_f32 v4, v4, v5
	ds_read2_b32 v[22:23], v28 offset0:206 offset1:239
	s_waitcnt lgkmcnt(0)
	v_cvt_pk_bf16_f32 v5, v22, v23
	v_lshl_add_u64 v[66:67], v[24:25], 0, v[8:9]
	ds_read2_b32 v[22:23], v28 offset0:16 offset1:49
	global_store_dwordx4 v[66:67], v[2:5], off
	v_or_b32_e32 v8, v76, v30
	v_lshlrev_b32_e32 v8, 12, v8
	s_waitcnt lgkmcnt(0)
	v_cvt_pk_bf16_f32 v2, v22, v23
	ds_read2_b32 v[4:5], v28 offset0:82 offset1:115
	s_waitcnt lgkmcnt(0)
	v_cvt_pk_bf16_f32 v3, v4, v5
	ds_read2_b32 v[4:5], v28 offset0:148 offset1:181
	s_waitcnt lgkmcnt(0)
	v_cvt_pk_bf16_f32 v4, v4, v5
	ds_read2_b32 v[22:23], v28 offset0:214 offset1:247
	s_waitcnt lgkmcnt(0)
	v_cvt_pk_bf16_f32 v5, v22, v23
	v_lshl_add_u64 v[66:67], v[24:25], 0, v[8:9]
	ds_read2_b32 v[22:23], v28 offset0:24 offset1:57
	global_store_dwordx4 v[66:67], v[2:5], off
	v_or_b32_e32 v8, v76, v31
	v_lshlrev_b32_e32 v8, 12, v8
	s_waitcnt lgkmcnt(0)
	v_cvt_pk_bf16_f32 v2, v22, v23
	ds_read2_b32 v[4:5], v28 offset0:90 offset1:123
	s_waitcnt lgkmcnt(0)
	v_cvt_pk_bf16_f32 v3, v4, v5
	ds_read2_b32 v[4:5], v28 offset0:156 offset1:189
	s_waitcnt lgkmcnt(0)
	v_cvt_pk_bf16_f32 v4, v4, v5
	ds_read2_b32 v[22:23], v28 offset0:222 offset1:255
	s_waitcnt lgkmcnt(0)
	v_cvt_pk_bf16_f32 v5, v22, v23
	v_lshl_add_u64 v[22:23], v[24:25], 0, v[8:9]
	global_store_dwordx4 v[22:23], v[2:5], off
	s_waitcnt lgkmcnt(0)

; template <int MODE  >
; __device__ __forceinline__ void transpose_item(const float* W, int K, int N, bf16_t* WT, int ldt, int koff, const float* ks, float* scr, int item, int lane) {
;     ...
;     float v[32]; const float* wp = W + (size_t)(k0 + (lane >> 5)) * N + nn; const bool nok = nn < N;
; #pragma unroll
;     for (int i = 0; i < 32; ++i) v[i] = nok ? wp[(size_t)(2 * i) * N] : 0.f;
.LBB0_24:
	s_andn2_saveexec_b64 s[18:19], s[18:19]
	s_cbranch_execz .LBB0_26
	v_add_u32_e32 v2, 0xffffcde0, v64
	v_and_b32_e32 v65, 0x1fc0, v2
	v_add_u32_e32 v2, 0xfff9bc00, v63
	v_and_b32_e32 v76, 0x7e0, v2
	v_or_b32_e32 v2, v65, v6
	v_readlane_b32 s40, v249, 5
	v_or_b32_e32 v4, v76, v1
	v_lshlrev_b32_e32 v8, 13, v2
	v_readlane_b32 s48, v249, 13
	v_readlane_b32 s49, v249, 14
	v_readlane_b32 s41, v249, 6
	v_readlane_b32 s42, v249, 7
	v_lshl_add_u64 v[2:3], s[48:49], 0, v[8:9]
	v_lshlrev_b32_e32 v8, 2, v4
	v_lshl_add_u64 v[2:3], v[2:3], 0, v[8:9]
	v_add_co_u32_e32 v4, vcc, 0x4000, v2
	v_readlane_b32 s43, v249, 8
	s_nop 0
	v_addc_co_u32_e32 v5, vcc, 0, v3, vcc
	v_add_co_u32_e32 v22, vcc, 0x8000, v2
	v_readlane_b32 s44, v249, 9
	s_nop 0
	v_addc_co_u32_e32 v23, vcc, 0, v3, vcc
	v_add_co_u32_e32 v24, vcc, 0xc000, v2
	v_readlane_b32 s45, v249, 10
	s_nop 0
	v_addc_co_u32_e32 v25, vcc, 0, v3, vcc
	v_add_co_u32_e32 v66, vcc, 0x10000, v2
	v_readlane_b32 s46, v249, 11
	s_nop 0
	v_addc_co_u32_e32 v67, vcc, 0, v3, vcc
	v_add_co_u32_e32 v68, vcc, 0x14000, v2
	v_readlane_b32 s47, v249, 12
	s_nop 0
	v_addc_co_u32_e32 v69, vcc, 0, v3, vcc
	v_add_co_u32_e32 v70, vcc, 0x18000, v2
	v_readlane_b32 s50, v249, 15
	s_nop 0
	v_addc_co_u32_e32 v71, vcc, 0, v3, vcc
	v_add_co_u32_e32 v72, vcc, 0x1c000, v2
	v_readlane_b32 s51, v249, 16
	s_nop 0
	v_addc_co_u32_e32 v73, vcc, 0, v3, vcc
	global_load_dword v8, v[2:3], off nt
	global_load_dword v77, v[4:5], off nt
	global_load_dword v78, v[22:23], off nt
	global_load_dword v79, v[24:25], off nt
	global_load_dword v80, v[66:67], off nt
	global_load_dword v81, v[68:69], off nt
	global_load_dword v82, v[70:71], off nt
	global_load_dword v83, v[72:73], off nt
	v_add_co_u32_e32 v4, vcc, 0x20000, v2
	v_readlane_b32 s52, v249, 17
	s_nop 0
	v_addc_co_u32_e32 v5, vcc, 0, v3, vcc
	v_add_co_u32_e32 v22, vcc, 0x24000, v2
	v_readlane_b32 s53, v249, 18
	s_nop 0
	v_addc_co_u32_e32 v23, vcc, 0, v3, vcc
	v_add_co_u32_e32 v24, vcc, 0x28000, v2
	v_readlane_b32 s54, v249, 19
	s_nop 0
	v_addc_co_u32_e32 v25, vcc, 0, v3, vcc
	v_add_co_u32_e32 v66, vcc, 0x2c000, v2
	v_readlane_b32 s55, v249, 20
	s_nop 0
	v_addc_co_u32_e32 v67, vcc, 0, v3, vcc
	v_add_co_u32_e32 v68, vcc, 0x30000, v2
	s_nop 1
	v_addc_co_u32_e32 v69, vcc, 0, v3, vcc
	v_add_co_u32_e32 v70, vcc, 0x34000, v2
	s_nop 1
	v_addc_co_u32_e32 v71, vcc, 0, v3, vcc
	v_add_co_u32_e32 v72, vcc, 0x38000, v2
	s_nop 1
	v_addc_co_u32_e32 v73, vcc, 0, v3, vcc
	v_add_co_u32_e32 v74, vcc, 0x3c000, v2
	s_nop 1
	v_addc_co_u32_e32 v75, vcc, 0, v3, vcc
	global_load_dword v84, v[4:5], off nt
	global_load_dword v85, v[22:23], off nt
	global_load_dword v86, v[24:25], off nt
	global_load_dword v87, v[66:67], off nt
	global_load_dword v88, v[68:69], off nt
	global_load_dword v89, v[70:71], off nt
	global_load_dword v90, v[72:73], off nt
	global_load_dword v91, v[74:75], off nt
	v_add_co_u32_e32 v4, vcc, 0x40000, v2
	s_nop 1
	v_addc_co_u32_e32 v5, vcc, 0, v3, vcc
	v_add_co_u32_e32 v22, vcc, 0x44000, v2
	s_nop 1
	v_addc_co_u32_e32 v23, vcc, 0, v3, vcc
	v_add_co_u32_e32 v24, vcc, 0x48000, v2
	s_nop 1
	v_addc_co_u32_e32 v25, vcc, 0, v3, vcc
	v_add_co_u32_e32 v66, vcc, 0x4c000, v2
	s_nop 1
	v_addc_co_u32_e32 v67, vcc, 0, v3, vcc
	v_add_co_u32_e32 v68, vcc, 0x50000, v2
	s_nop 1
	v_addc_co_u32_e32 v69, vcc, 0, v3, vcc
	v_add_co_u32_e32 v70, vcc, 0x54000, v2
	s_nop 1
	v_addc_co_u32_e32 v71, vcc, 0, v3, vcc
	v_add_co_u32_e32 v72, vcc, 0x58000, v2
	s_nop 1
	v_addc_co_u32_e32 v73, vcc, 0, v3, vcc
	v_add_co_u32_e32 v74, vcc, 0x5c000, v2
	s_nop 1
	v_addc_co_u32_e32 v75, vcc, 0, v3, vcc
	global_load_dword v92, v[4:5], off nt
	global_load_dword v93, v[22:23], off nt
	global_load_dword v94, v[24:25], off nt
	global_load_dword v95, v[66:67], off nt
	global_load_dword v96, v[68:69], off nt
	global_load_dword v97, v[70:71], off nt
	global_load_dword v98, v[72:73], off nt
	s_nop 0
	global_load_dword v74, v[74:75], off nt
	v_add_co_u32_e32 v4, vcc, 0x60000, v2
	s_nop 1
	v_addc_co_u32_e32 v5, vcc, 0, v3, vcc
	v_add_co_u32_e32 v22, vcc, 0x64000, v2
	s_nop 1
	v_addc_co_u32_e32 v23, vcc, 0, v3, vcc
	v_add_co_u32_e32 v24, vcc, 0x68000, v2
	s_nop 1
	v_addc_co_u32_e32 v25, vcc, 0, v3, vcc
	v_add_co_u32_e32 v66, vcc, 0x6c000, v2
	s_nop 1
	v_addc_co_u32_e32 v67, vcc, 0, v3, vcc
	v_add_co_u32_e32 v68, vcc, 0x70000, v2
	s_nop 1
	v_addc_co_u32_e32 v69, vcc, 0, v3, vcc
	v_add_co_u32_e32 v70, vcc, 0x74000, v2
	s_nop 1
	v_addc_co_u32_e32 v71, vcc, 0, v3, vcc
	v_add_co_u32_e32 v72, vcc, 0x78000, v2
	s_nop 1
	v_addc_co_u32_e32 v73, vcc, 0, v3, vcc
	v_add_co_u32_e32 v2, vcc, 0x7c000, v2
	s_nop 1
	v_addc_co_u32_e32 v3, vcc, 0, v3, vcc
	global_load_dword v4, v[4:5], off nt
	s_nop 0
	global_load_dword v5, v[22:23], off nt
	s_nop 0
	global_load_dword v22, v[24:25], off nt
	global_load_dword v23, v[66:67], off nt
	s_nop 0
	global_load_dword v24, v[68:69], off nt
	global_load_dword v25, v[70:71], off nt
	global_load_dword v66, v[72:73], off nt
	s_nop 0
	global_load_dword v2, v[2:3], off nt
	v_add_u32_e32 v3, 0x400, v26
	s_waitcnt vmcnt(30)
; __device__ __forceinline__ unsigned cvt_pk_bf16(float lo, float hi) { unsigned r; asm volatile("v_cvt_pk_bf16_f32 %0, %1, %2" : "=v"(r) : "v"(lo), "v"(hi)); return r; }
; #define LDS_WAIT() asm volatile("s_waitcnt lgkmcnt(0)" ::: "memory")
; template <int MODE  >
; __device__ __forceinline__ void transpose_item(const float* W, int K, int N, bf16_t* WT, int ldt, int koff, const float* ks, float* scr, int item, int lane) {
;     ...
;     for (int i = 0; i < 32; ++i) { const int kk = 2 * i + (lane >> 5); float x = v[i]; if (MODE != 0) x *= ks[k0 + kk]; scr[kk * 33 + (lane & 31)] = x; }
;     LDS_WAIT(); asm volatile("" ::: "memory");
;     const int c = lane & 7;
; #pragma unroll
;     for (int j = 0; j < 4; ++j) { const int nl = (lane >> 3) + 8 * j, n = n0 + nl; const float* s = scr + (8 * c) * 33 + nl;
;         u32x4 o; o.x = cvt_pk_bf16(s[0 * 33], s[1 * 33]); o.y = cvt_pk_bf16(s[2 * 33], s[3 * 33]); o.z = cvt_pk_bf16(s[4 * 33], s[5 * 33]); o.w = cvt_pk_bf16(s[6 * 33], s[7 * 33]);
;         int dst = n; if (MODE == 1) dst = n < 7680 ? n : (n < 7696 ? ZAG + (n - 7680) : n - 16);
;         if (n < N) *(u32x4*)(WT + (size_t)dst * ldt + koff + k0 + 8 * c) = o; }
	ds_write2_b32 v26, v8, v77 offset1:66
	s_waitcnt vmcnt(28)
	ds_write2_b32 v26, v78, v79 offset0:132 offset1:198
	s_waitcnt vmcnt(26)
	ds_write2_b32 v3, v80, v81 offset0:8 offset1:74
	s_waitcnt vmcnt(24)
	ds_write2_b32 v3, v82, v83 offset0:140 offset1:206
	v_add_u32_e32 v3, 0x800, v26
	s_waitcnt vmcnt(22)
	ds_write2_b32 v3, v84, v85 offset0:16 offset1:82
	s_waitcnt vmcnt(20)
	ds_write2_b32 v3, v86, v87 offset0:148 offset1:214
	v_add_u32_e32 v3, 0xc00, v26
	s_waitcnt vmcnt(18)
	ds_write2_b32 v3, v88, v89 offset0:24 offset1:90
	s_waitcnt vmcnt(16)
	ds_write2_b32 v3, v90, v91 offset0:156 offset1:222
	v_add_u32_e32 v3, 0x1000, v26
	s_waitcnt vmcnt(14)
	ds_write2_b32 v3, v92, v93 offset0:32 offset1:98
	s_waitcnt vmcnt(12)
	ds_write2_b32 v3, v94, v95 offset0:164 offset1:230
	v_add_u32_e32 v3, 0x1400, v26
	s_waitcnt vmcnt(10)
	ds_write2_b32 v3, v96, v97 offset0:40 offset1:106
	s_waitcnt vmcnt(8)
	ds_write2_b32 v3, v98, v74 offset0:172 offset1:238
	v_add_u32_e32 v3, 0x1800, v26
	s_waitcnt vmcnt(6)
	ds_write2_b32 v3, v4, v5 offset0:48 offset1:114
	s_waitcnt vmcnt(4)
	ds_write2_b32 v3, v22, v23 offset0:180 offset1:246
	v_add_u32_e32 v3, 0x1c00, v26
	s_waitcnt vmcnt(2)
	ds_write2_b32 v3, v24, v25 offset0:56 offset1:122
	s_waitcnt vmcnt(0)
	ds_write2_b32 v3, v66, v2 offset0:188 offset1:254
	s_waitcnt lgkmcnt(0)
	v_lshlrev_b32_e32 v8, 1, v65
	ds_read2_b32 v[2:3], v28 offset1:33
	v_lshl_add_u64 v[24:25], v[16:17], 0, v[8:9]
	v_or_b32_e32 v8, v76, v27
	s_waitcnt lgkmcnt(0)
	v_cvt_pk_bf16_f32 v2, v2, v3
	ds_read2_b32 v[4:5], v28 offset0:66 offset1:99
	v_mul_u32_u24_e32 v8, 0xc00, v8
	s_waitcnt lgkmcnt(0)
	v_cvt_pk_bf16_f32 v3, v4, v5
	ds_read2_b32 v[4:5], v28 offset0:132 offset1:165
	v_lshlrev_b32_e32 v8, 1, v8
	s_waitcnt lgkmcnt(0)
	v_cvt_pk_bf16_f32 v4, v4, v5
	ds_read2_b32 v[22:23], v28 offset0:198 offset1:231
	s_waitcnt lgkmcnt(0)
	v_cvt_pk_bf16_f32 v5, v22, v23
	v_lshl_add_u64 v[66:67], v[24:25], 0, v[8:9]
	v_or_b32_e32 v8, v76, v29
	ds_read2_b32 v[22:23], v28 offset0:8 offset1:41
	global_store_dwordx4 v[66:67], v[2:5], off
	v_mul_u32_u24_e32 v8, 0xc00, v8
	v_lshlrev_b32_e32 v8, 1, v8
	s_waitcnt lgkmcnt(0)
	v_cvt_pk_bf16_f32 v2, v22, v23
	ds_read2_b32 v[4:5], v28 offset0:74 offset1:107
	s_waitcnt lgkmcnt(0)
	v_cvt_pk_bf16_f32 v3, v4, v5
	ds_read2_b32 v[4:5], v28 offset0:140 offset1:173
	s_waitcnt lgkmcnt(0)
	v_cvt_pk_bf16_f32 v4, v4, v5
	ds_read2_b32 v[22:23], v28 offset0:206 offset1:239
	s_waitcnt lgkmcnt(0)
	v_cvt_pk_bf16_f32 v5, v22, v23
	v_lshl_add_u64 v[66:67], v[24:25], 0, v[8:9]
	v_or_b32_e32 v8, v76, v30
	ds_read2_b32 v[22:23], v28 offset0:16 offset1:49
	global_store_dwordx4 v[66:67], v[2:5], off
	v_mul_u32_u24_e32 v8, 0xc00, v8
	v_lshlrev_b32_e32 v8, 1, v8
	s_waitcnt lgkmcnt(0)
	v_cvt_pk_bf16_f32 v2, v22, v23
	ds_read2_b32 v[4:5], v28 offset0:82 offset1:115
	s_waitcnt lgkmcnt(0)
	v_cvt_pk_bf16_f32 v3, v4, v5
	ds_read2_b32 v[4:5], v28 offset0:148 offset1:181
	s_waitcnt lgkmcnt(0)
	v_cvt_pk_bf16_f32 v4, v4, v5
	ds_read2_b32 v[22:23], v28 offset0:214 offset1:247
	s_waitcnt lgkmcnt(0)
	v_cvt_pk_bf16_f32 v5, v22, v23
	v_lshl_add_u64 v[66:67], v[24:25], 0, v[8:9]
	ds_read2_b32 v[22:23], v28 offset0:24 offset1:57
	global_store_dwordx4 v[66:67], v[2:5], off
	v_or_b32_e32 v8, v76, v31
	v_mul_u32_u24_e32 v8, 0xc00, v8
	s_waitcnt lgkmcnt(0)
	v_cvt_pk_bf16_f32 v2, v22, v23
	ds_read2_b32 v[4:5], v28 offset0:90 offset1:123
	s_waitcnt lgkmcnt(0)
	v_cvt_pk_bf16_f32 v3, v4, v5
	ds_read2_b32 v[4:5], v28 offset0:156 offset1:189
	s_waitcnt lgkmcnt(0)
	v_cvt_pk_bf16_f32 v4, v4, v5
	ds_read2_b32 v[22:23], v28 offset0:222 offset1:255
	v_lshlrev_b32_e32 v8, 1, v8
	s_waitcnt lgkmcnt(0)
	v_cvt_pk_bf16_f32 v5, v22, v23
	v_lshl_add_u64 v[22:23], v[24:25], 0, v[8:9]
	global_store_dwordx4 v[22:23], v[2:5], off
	s_waitcnt lgkmcnt(0)

; template <int MODE  >
; __device__ __forceinline__ void transpose_item(const float* W, int K, int N, bf16_t* WT, int ldt, int koff, const float* ks, float* scr, int item, int lane) {
;     ...
;     float v[32]; const float* wp = W + (size_t)(k0 + (lane >> 5)) * N + nn; const bool nok = nn < N;
; #pragma unroll
;     for (int i = 0; i < 32; ++i) v[i] = nok ? wp[(size_t)(2 * i) * N] : 0.f;
.LBB0_27:
	s_andn2_saveexec_b64 s[16:17], s[16:17]
	s_cbranch_execz .LBB0_29
	v_add_u32_e32 v2, 0xffffd1e0, v64
	v_and_b32_e32 v65, 0x1fc0, v2
	v_add_u32_e32 v2, 0xfffa3c00, v63
	v_and_b32_e32 v76, 0x7e0, v2
	v_or_b32_e32 v2, v65, v6
	v_readlane_b32 s40, v249, 5
	v_or_b32_e32 v4, v76, v1
	v_lshlrev_b32_e32 v8, 13, v2
	v_readlane_b32 s46, v249, 11
	v_readlane_b32 s47, v249, 12
	v_readlane_b32 s41, v249, 6
	v_readlane_b32 s42, v249, 7
	v_lshl_add_u64 v[2:3], s[46:47], 0, v[8:9]
	v_lshlrev_b32_e32 v8, 2, v4
	v_lshl_add_u64 v[2:3], v[2:3], 0, v[8:9]
	v_add_co_u32_e32 v4, vcc, 0x4000, v2
	v_readlane_b32 s43, v249, 8
	s_nop 0
	v_addc_co_u32_e32 v5, vcc, 0, v3, vcc
	v_add_co_u32_e32 v22, vcc, 0x8000, v2
	v_readlane_b32 s44, v249, 9
	s_nop 0
	v_addc_co_u32_e32 v23, vcc, 0, v3, vcc
	v_add_co_u32_e32 v24, vcc, 0xc000, v2
	v_readlane_b32 s45, v249, 10
	s_nop 0
	v_addc_co_u32_e32 v25, vcc, 0, v3, vcc
	v_add_co_u32_e32 v66, vcc, 0x10000, v2
	v_readlane_b32 s48, v249, 13
	s_nop 0
	v_addc_co_u32_e32 v67, vcc, 0, v3, vcc
	v_add_co_u32_e32 v68, vcc, 0x14000, v2
	v_readlane_b32 s49, v249, 14
	s_nop 0
	v_addc_co_u32_e32 v69, vcc, 0, v3, vcc
	v_add_co_u32_e32 v70, vcc, 0x18000, v2
	v_readlane_b32 s50, v249, 15
	s_nop 0
	v_addc_co_u32_e32 v71, vcc, 0, v3, vcc
	v_add_co_u32_e32 v72, vcc, 0x1c000, v2
	v_readlane_b32 s51, v249, 16
	s_nop 0
	v_addc_co_u32_e32 v73, vcc, 0, v3, vcc
	global_load_dword v8, v[2:3], off nt
	global_load_dword v77, v[4:5], off nt
	global_load_dword v78, v[22:23], off nt
	global_load_dword v79, v[24:25], off nt
	global_load_dword v80, v[66:67], off nt
	global_load_dword v81, v[68:69], off nt
	global_load_dword v82, v[70:71], off nt
	global_load_dword v83, v[72:73], off nt
	v_add_co_u32_e32 v4, vcc, 0x20000, v2
	v_readlane_b32 s52, v249, 17
	s_nop 0
	v_addc_co_u32_e32 v5, vcc, 0, v3, vcc
	v_add_co_u32_e32 v22, vcc, 0x24000, v2
	v_readlane_b32 s53, v249, 18
	s_nop 0
	v_addc_co_u32_e32 v23, vcc, 0, v3, vcc
	v_add_co_u32_e32 v24, vcc, 0x28000, v2
	v_readlane_b32 s54, v249, 19
	s_nop 0
	v_addc_co_u32_e32 v25, vcc, 0, v3, vcc
	v_add_co_u32_e32 v66, vcc, 0x2c000, v2
	v_readlane_b32 s55, v249, 20
	s_nop 0
	v_addc_co_u32_e32 v67, vcc, 0, v3, vcc
	v_add_co_u32_e32 v68, vcc, 0x30000, v2
	s_nop 1
	v_addc_co_u32_e32 v69, vcc, 0, v3, vcc
	v_add_co_u32_e32 v70, vcc, 0x34000, v2
	s_nop 1
	v_addc_co_u32_e32 v71, vcc, 0, v3, vcc
	v_add_co_u32_e32 v72, vcc, 0x38000, v2
	s_nop 1
	v_addc_co_u32_e32 v73, vcc, 0, v3, vcc
	v_add_co_u32_e32 v74, vcc, 0x3c000, v2
	s_nop 1
	v_addc_co_u32_e32 v75, vcc, 0, v3, vcc
	global_load_dword v84, v[4:5], off nt
	global_load_dword v85, v[22:23], off nt
	global_load_dword v86, v[24:25], off nt
	global_load_dword v87, v[66:67], off nt
	global_load_dword v88, v[68:69], off nt
	global_load_dword v89, v[70:71], off nt
	global_load_dword v90, v[72:73], off nt
	global_load_dword v91, v[74:75], off nt
	v_add_co_u32_e32 v4, vcc, 0x40000, v2
	s_nop 1
	v_addc_co_u32_e32 v5, vcc, 0, v3, vcc
	v_add_co_u32_e32 v22, vcc, 0x44000, v2
	s_nop 1
	v_addc_co_u32_e32 v23, vcc, 0, v3, vcc
	v_add_co_u32_e32 v24, vcc, 0x48000, v2
	s_nop 1
	v_addc_co_u32_e32 v25, vcc, 0, v3, vcc
	v_add_co_u32_e32 v66, vcc, 0x4c000, v2
	s_nop 1
	v_addc_co_u32_e32 v67, vcc, 0, v3, vcc
	v_add_co_u32_e32 v68, vcc, 0x50000, v2
	s_nop 1
	v_addc_co_u32_e32 v69, vcc, 0, v3, vcc
	v_add_co_u32_e32 v70, vcc, 0x54000, v2
	s_nop 1
	v_addc_co_u32_e32 v71, vcc, 0, v3, vcc
	v_add_co_u32_e32 v72, vcc, 0x58000, v2
	s_nop 1
	v_addc_co_u32_e32 v73, vcc, 0, v3, vcc
	v_add_co_u32_e32 v74, vcc, 0x5c000, v2
	s_nop 1
	v_addc_co_u32_e32 v75, vcc, 0, v3, vcc
	global_load_dword v92, v[4:5], off nt
	global_load_dword v93, v[22:23], off nt
	global_load_dword v94, v[24:25], off nt
	global_load_dword v95, v[66:67], off nt
	global_load_dword v96, v[68:69], off nt
	global_load_dword v97, v[70:71], off nt
	global_load_dword v98, v[72:73], off nt
	s_nop 0
	global_load_dword v74, v[74:75], off nt
	v_add_co_u32_e32 v4, vcc, 0x60000, v2
	s_nop 1
	v_addc_co_u32_e32 v5, vcc, 0, v3, vcc
	v_add_co_u32_e32 v22, vcc, 0x64000, v2
	s_nop 1
	v_addc_co_u32_e32 v23, vcc, 0, v3, vcc
	v_add_co_u32_e32 v24, vcc, 0x68000, v2
	s_nop 1
	v_addc_co_u32_e32 v25, vcc, 0, v3, vcc
	v_add_co_u32_e32 v66, vcc, 0x6c000, v2
	s_nop 1
	v_addc_co_u32_e32 v67, vcc, 0, v3, vcc
	v_add_co_u32_e32 v68, vcc, 0x70000, v2
	s_nop 1
	v_addc_co_u32_e32 v69, vcc, 0, v3, vcc
	v_add_co_u32_e32 v70, vcc, 0x74000, v2
	s_nop 1
	v_addc_co_u32_e32 v71, vcc, 0, v3, vcc
	v_add_co_u32_e32 v72, vcc, 0x78000, v2
	s_nop 1
	v_addc_co_u32_e32 v73, vcc, 0, v3, vcc
	v_add_co_u32_e32 v2, vcc, 0x7c000, v2
	s_nop 1
	v_addc_co_u32_e32 v3, vcc, 0, v3, vcc
	global_load_dword v4, v[4:5], off nt
	s_nop 0
	global_load_dword v5, v[22:23], off nt
	s_nop 0
	global_load_dword v22, v[24:25], off nt
	global_load_dword v23, v[66:67], off nt
	s_nop 0
	global_load_dword v24, v[68:69], off nt
	global_load_dword v25, v[70:71], off nt
	global_load_dword v66, v[72:73], off nt
	s_nop 0
	global_load_dword v2, v[2:3], off nt
	v_add_u32_e32 v3, 0x400, v26
	s_waitcnt vmcnt(30)
; __device__ __forceinline__ unsigned cvt_pk_bf16(float lo, float hi) { unsigned r; asm volatile("v_cvt_pk_bf16_f32 %0, %1, %2" : "=v"(r) : "v"(lo), "v"(hi)); return r; }
; #define LDS_WAIT() asm volatile("s_waitcnt lgkmcnt(0)" ::: "memory")
; template <int MODE  >
; __device__ __forceinline__ void transpose_item(const float* W, int K, int N, bf16_t* WT, int ldt, int koff, const float* ks, float* scr, int item, int lane) {
;     ...
;     for (int i = 0; i < 32; ++i) { const int kk = 2 * i + (lane >> 5); float x = v[i]; if (MODE != 0) x *= ks[k0 + kk]; scr[kk * 33 + (lane & 31)] = x; }
;     LDS_WAIT(); asm volatile("" ::: "memory");
;     const int c = lane & 7;
; #pragma unroll
;     for (int j = 0; j < 4; ++j) { const int nl = (lane >> 3) + 8 * j, n = n0 + nl; const float* s = scr + (8 * c) * 33 + nl;
;         u32x4 o; o.x = cvt_pk_bf16(s[0 * 33], s[1 * 33]); o.y = cvt_pk_bf16(s[2 * 33], s[3 * 33]); o.z = cvt_pk_bf16(s[4 * 33], s[5 * 33]); o.w = cvt_pk_bf16(s[6 * 33], s[7 * 33]);
;         int dst = n; if (MODE == 1) dst = n < 7680 ? n : (n < 7696 ? ZAG + (n - 7680) : n - 16);
;         if (n < N) *(u32x4*)(WT + (size_t)dst * ldt + koff + k0 + 8 * c) = o; }
	ds_write2_b32 v26, v8, v77 offset1:66
	s_waitcnt vmcnt(28)
	ds_write2_b32 v26, v78, v79 offset0:132 offset1:198
	s_waitcnt vmcnt(26)
	ds_write2_b32 v3, v80, v81 offset0:8 offset1:74
	s_waitcnt vmcnt(24)
	ds_write2_b32 v3, v82, v83 offset0:140 offset1:206
	v_add_u32_e32 v3, 0x800, v26
	s_waitcnt vmcnt(22)
	ds_write2_b32 v3, v84, v85 offset0:16 offset1:82
	s_waitcnt vmcnt(20)
	ds_write2_b32 v3, v86, v87 offset0:148 offset1:214
	v_add_u32_e32 v3, 0xc00, v26
	s_waitcnt vmcnt(18)
	ds_write2_b32 v3, v88, v89 offset0:24 offset1:90
	s_waitcnt vmcnt(16)
	ds_write2_b32 v3, v90, v91 offset0:156 offset1:222
	v_add_u32_e32 v3, 0x1000, v26
	s_waitcnt vmcnt(14)
	ds_write2_b32 v3, v92, v93 offset0:32 offset1:98
	s_waitcnt vmcnt(12)
	ds_write2_b32 v3, v94, v95 offset0:164 offset1:230
	v_add_u32_e32 v3, 0x1400, v26
	s_waitcnt vmcnt(10)
	ds_write2_b32 v3, v96, v97 offset0:40 offset1:106
	s_waitcnt vmcnt(8)
	ds_write2_b32 v3, v98, v74 offset0:172 offset1:238
	v_add_u32_e32 v3, 0x1800, v26
	s_waitcnt vmcnt(6)
	ds_write2_b32 v3, v4, v5 offset0:48 offset1:114
	s_waitcnt vmcnt(4)
	ds_write2_b32 v3, v22, v23 offset0:180 offset1:246
	v_add_u32_e32 v3, 0x1c00, v26
	s_waitcnt vmcnt(2)
	ds_write2_b32 v3, v24, v25 offset0:56 offset1:122
	s_waitcnt vmcnt(0)
	ds_write2_b32 v3, v66, v2 offset0:188 offset1:254
	s_waitcnt lgkmcnt(0)
	v_lshlrev_b32_e32 v8, 1, v65
	ds_read2_b32 v[2:3], v28 offset1:33
	v_lshl_add_u64 v[24:25], v[18:19], 0, v[8:9]
	v_or_b32_e32 v8, v76, v27
	s_waitcnt lgkmcnt(0)
	v_cvt_pk_bf16_f32 v2, v2, v3
	ds_read2_b32 v[4:5], v28 offset0:66 offset1:99
	v_mul_u32_u24_e32 v8, 0xc00, v8
	s_waitcnt lgkmcnt(0)
	v_cvt_pk_bf16_f32 v3, v4, v5
	ds_read2_b32 v[4:5], v28 offset0:132 offset1:165
	v_lshlrev_b32_e32 v8, 1, v8
	s_waitcnt lgkmcnt(0)
	v_cvt_pk_bf16_f32 v4, v4, v5
	ds_read2_b32 v[22:23], v28 offset0:198 offset1:231
	s_waitcnt lgkmcnt(0)
	v_cvt_pk_bf16_f32 v5, v22, v23
	v_lshl_add_u64 v[66:67], v[24:25], 0, v[8:9]
	v_or_b32_e32 v8, v76, v29
	ds_read2_b32 v[22:23], v28 offset0:8 offset1:41
	global_store_dwordx4 v[66:67], v[2:5], off
	v_mul_u32_u24_e32 v8, 0xc00, v8
	v_lshlrev_b32_e32 v8, 1, v8
	s_waitcnt lgkmcnt(0)
	v_cvt_pk_bf16_f32 v2, v22, v23
	ds_read2_b32 v[4:5], v28 offset0:74 offset1:107
	s_waitcnt lgkmcnt(0)
	v_cvt_pk_bf16_f32 v3, v4, v5
	ds_read2_b32 v[4:5], v28 offset0:140 offset1:173
	s_waitcnt lgkmcnt(0)
	v_cvt_pk_bf16_f32 v4, v4, v5
	ds_read2_b32 v[22:23], v28 offset0:206 offset1:239
	s_waitcnt lgkmcnt(0)
	v_cvt_pk_bf16_f32 v5, v22, v23
	v_lshl_add_u64 v[66:67], v[24:25], 0, v[8:9]
	v_or_b32_e32 v8, v76, v30
	ds_read2_b32 v[22:23], v28 offset0:16 offset1:49
	global_store_dwordx4 v[66:67], v[2:5], off
	v_mul_u32_u24_e32 v8, 0xc00, v8
	v_lshlrev_b32_e32 v8, 1, v8
	s_waitcnt lgkmcnt(0)
	v_cvt_pk_bf16_f32 v2, v22, v23
	ds_read2_b32 v[4:5], v28 offset0:82 offset1:115
	s_waitcnt lgkmcnt(0)
	v_cvt_pk_bf16_f32 v3, v4, v5
	ds_read2_b32 v[4:5], v28 offset0:148 offset1:181
	s_waitcnt lgkmcnt(0)
	v_cvt_pk_bf16_f32 v4, v4, v5
	ds_read2_b32 v[22:23], v28 offset0:214 offset1:247
	s_waitcnt lgkmcnt(0)
	v_cvt_pk_bf16_f32 v5, v22, v23
	v_lshl_add_u64 v[66:67], v[24:25], 0, v[8:9]
	ds_read2_b32 v[22:23], v28 offset0:24 offset1:57
	global_store_dwordx4 v[66:67], v[2:5], off
	v_or_b32_e32 v8, v76, v31
	v_mul_u32_u24_e32 v8, 0xc00, v8
	s_waitcnt lgkmcnt(0)
	v_cvt_pk_bf16_f32 v2, v22, v23
	ds_read2_b32 v[4:5], v28 offset0:90 offset1:123
	s_waitcnt lgkmcnt(0)
	v_cvt_pk_bf16_f32 v3, v4, v5
	ds_read2_b32 v[4:5], v28 offset0:156 offset1:189
	s_waitcnt lgkmcnt(0)
	v_cvt_pk_bf16_f32 v4, v4, v5
	ds_read2_b32 v[22:23], v28 offset0:222 offset1:255
	v_lshlrev_b32_e32 v8, 1, v8
	s_waitcnt lgkmcnt(0)
	v_cvt_pk_bf16_f32 v5, v22, v23
	v_lshl_add_u64 v[22:23], v[24:25], 0, v[8:9]
	global_store_dwordx4 v[22:23], v[2:5], off
	s_waitcnt lgkmcnt(0)

; template <int MODE  >
; __device__ __forceinline__ void transpose_item(const float* W, int K, int N, bf16_t* WT, int ldt, int koff, const float* ks, float* scr, int item, int lane) {
;     const int nblk = (N + 31) / 32, kb = item / nblk, nb = item % nblk, k0 = 64 * kb, n0 = 32 * nb;
;     const int nn = n0 + (lane & 31);
;     float v[32]; const float* wp = W + (size_t)(k0 + (lane >> 5)) * N + nn; const bool nok = nn < N;
; #pragma unroll
;     for (int i = 0; i < 32; ++i) v[i] = nok ? wp[(size_t)(2 * i) * N] : 0.f;
.LBB0_30:
	s_andn2_saveexec_b64 s[16:17], s[4:5]
	s_cbranch_execz .LBB0_11
	v_mul_hi_i32 v2, v64, s29
	v_add_u32_e32 v2, v2, v64
	v_lshrrev_b32_e32 v3, 31, v2
	v_ashrrev_i32_e32 v2, 8, v2
	v_add_u32_e32 v2, v2, v3
	v_mul_i32_i24_e32 v8, 0x171, v2
	v_lshlrev_b32_e32 v22, 6, v2
	v_lshlrev_b32_e32 v3, 5, v8
	v_add_u32_e32 v2, v1, v63
	v_sub_u32_e32 v24, v2, v3
	v_or_b32_e32 v2, v22, v6
	v_mov_b64_e32 v[4:5], s[76:77]
	v_mad_i64_i32 v[4:5], s[4:5], v2, s30, v[4:5]
	v_ashrrev_i32_e32 v25, 31, v24
	v_lshl_add_u64 v[4:5], v[24:25], 2, v[4:5]
	v_cmp_gt_i32_e64 s[4:5], s31, v24
	v_mov_b32_e32 v24, 0
	v_mov_b32_e32 v23, 0
	s_and_saveexec_b64 s[18:19], s[4:5]
	s_cbranch_execz .LBB0_33
	global_load_dword v23, v[4:5], off nt
.LBB0_33:
	s_or_b64 exec, exec, s[18:19]
	s_and_saveexec_b64 s[18:19], s[4:5]
	s_cbranch_execz .LBB0_35
	v_add_co_u32_e32 v24, vcc, 0x17000, v4
	s_nop 1
	v_addc_co_u32_e32 v25, vcc, 0, v5, vcc
	global_load_dword v24, v[24:25], off offset:128 nt
.LBB0_35:
	s_or_b64 exec, exec, s[18:19]
	v_mov_b32_e32 v25, 0
	v_mov_b32_e32 v65, 0
	s_and_saveexec_b64 s[18:19], s[4:5]
	s_cbranch_execz .LBB0_37
	v_add_co_u32_e32 v66, vcc, 0x2e000, v4
	s_nop 1
	v_addc_co_u32_e32 v67, vcc, 0, v5, vcc
	global_load_dword v65, v[66:67], off offset:256 nt
.LBB0_37:
	s_or_b64 exec, exec, s[18:19]
	s_and_saveexec_b64 s[18:19], s[4:5]
	s_cbranch_execz .LBB0_39
	v_add_co_u32_e32 v66, vcc, 0x45000, v4
	s_nop 1
	v_addc_co_u32_e32 v67, vcc, 0, v5, vcc
	global_load_dword v25, v[66:67], off offset:384 nt
.LBB0_39:
	s_or_b64 exec, exec, s[18:19]
	v_mov_b32_e32 v66, 0
	v_mov_b32_e32 v67, 0
	s_and_saveexec_b64 s[18:19], s[4:5]
	s_cbranch_execz .LBB0_41
	v_add_co_u32_e32 v68, vcc, 0x5c000, v4
	s_nop 1
	v_addc_co_u32_e32 v69, vcc, 0, v5, vcc
	global_load_dword v67, v[68:69], off offset:512 nt
.LBB0_41:
	s_or_b64 exec, exec, s[18:19]
	s_and_saveexec_b64 s[18:19], s[4:5]
	s_cbranch_execz .LBB0_43
	v_add_co_u32_e32 v68, vcc, 0x73000, v4
	s_nop 1
	v_addc_co_u32_e32 v69, vcc, 0, v5, vcc
	global_load_dword v66, v[68:69], off offset:640 nt
.LBB0_43:
	s_or_b64 exec, exec, s[18:19]
	v_mov_b32_e32 v68, 0
	v_mov_b32_e32 v69, 0
	s_and_saveexec_b64 s[18:19], s[4:5]
	s_cbranch_execz .LBB0_45
	v_add_co_u32_e32 v70, vcc, 0x8a000, v4
	s_nop 1
	v_addc_co_u32_e32 v71, vcc, 0, v5, vcc
	global_load_dword v69, v[70:71], off offset:768 nt
.LBB0_45:
	s_or_b64 exec, exec, s[18:19]
	s_and_saveexec_b64 s[18:19], s[4:5]
	s_cbranch_execz .LBB0_47
	v_add_co_u32_e32 v70, vcc, 0xa1000, v4
	s_nop 1
	v_addc_co_u32_e32 v71, vcc, 0, v5, vcc
	global_load_dword v68, v[70:71], off offset:896 nt
.LBB0_47:
	s_or_b64 exec, exec, s[18:19]
	v_mov_b32_e32 v70, 0
	v_mov_b32_e32 v71, 0
	s_and_saveexec_b64 s[18:19], s[4:5]
	s_cbranch_execz .LBB0_49
	v_add_co_u32_e32 v72, vcc, 0xb8000, v4
	s_nop 1
	v_addc_co_u32_e32 v73, vcc, 0, v5, vcc
	global_load_dword v71, v[72:73], off offset:1024 nt
.LBB0_49:
	s_or_b64 exec, exec, s[18:19]
	s_and_saveexec_b64 s[18:19], s[4:5]
	s_cbranch_execz .LBB0_51
	v_add_co_u32_e32 v72, vcc, 0xcf000, v4
	s_nop 1
	v_addc_co_u32_e32 v73, vcc, 0, v5, vcc
	global_load_dword v70, v[72:73], off offset:1152 nt
.LBB0_51:
	s_or_b64 exec, exec, s[18:19]
	v_mov_b32_e32 v72, 0
	v_mov_b32_e32 v73, 0
	s_and_saveexec_b64 s[18:19], s[4:5]
	s_cbranch_execz .LBB0_53
	v_add_co_u32_e32 v74, vcc, 0xe6000, v4
	s_nop 1
	v_addc_co_u32_e32 v75, vcc, 0, v5, vcc
	global_load_dword v73, v[74:75], off offset:1280 nt
.LBB0_53:
	s_or_b64 exec, exec, s[18:19]
	s_and_saveexec_b64 s[18:19], s[4:5]
	s_cbranch_execz .LBB0_55
	v_add_co_u32_e32 v74, vcc, 0xfd000, v4
	s_nop 1
	v_addc_co_u32_e32 v75, vcc, 0, v5, vcc
	global_load_dword v72, v[74:75], off offset:1408 nt
.LBB0_55:
	s_or_b64 exec, exec, s[18:19]
	v_mov_b32_e32 v74, 0
	v_mov_b32_e32 v75, 0
	s_and_saveexec_b64 s[18:19], s[4:5]
	s_cbranch_execz .LBB0_57
	v_add_co_u32_e32 v76, vcc, 0x114000, v4
	s_nop 1
	v_addc_co_u32_e32 v77, vcc, 0, v5, vcc
	global_load_dword v75, v[76:77], off offset:1536 nt
.LBB0_57:
	s_or_b64 exec, exec, s[18:19]
	s_and_saveexec_b64 s[18:19], s[4:5]
	s_cbranch_execz .LBB0_59
	v_add_co_u32_e32 v76, vcc, 0x12b000, v4
	s_nop 1
	v_addc_co_u32_e32 v77, vcc, 0, v5, vcc
	global_load_dword v74, v[76:77], off offset:1664 nt
.LBB0_59:
	s_or_b64 exec, exec, s[18:19]
	v_mov_b32_e32 v76, 0
	v_mov_b32_e32 v77, 0
	s_and_saveexec_b64 s[18:19], s[4:5]
	s_cbranch_execz .LBB0_61
	v_add_co_u32_e32 v78, vcc, 0x142000, v4
	s_nop 1
	v_addc_co_u32_e32 v79, vcc, 0, v5, vcc
	global_load_dword v77, v[78:79], off offset:1792 nt
.LBB0_61:
	s_or_b64 exec, exec, s[18:19]
	s_and_saveexec_b64 s[18:19], s[4:5]
	s_cbranch_execz .LBB0_63
	v_add_co_u32_e32 v78, vcc, 0x159000, v4
	s_nop 1
	v_addc_co_u32_e32 v79, vcc, 0, v5, vcc
	global_load_dword v76, v[78:79], off offset:1920 nt
.LBB0_63:
	s_or_b64 exec, exec, s[18:19]
	v_mov_b32_e32 v78, 0
	v_mov_b32_e32 v79, 0
	s_and_saveexec_b64 s[18:19], s[4:5]
	s_cbranch_execz .LBB0_65
	v_add_co_u32_e32 v80, vcc, 0x170000, v4
	s_nop 1
	v_addc_co_u32_e32 v81, vcc, 0, v5, vcc
	global_load_dword v79, v[80:81], off offset:2048 nt
.LBB0_65:
	s_or_b64 exec, exec, s[18:19]
	s_and_saveexec_b64 s[18:19], s[4:5]
	s_cbranch_execz .LBB0_67
	v_add_co_u32_e32 v80, vcc, 0x187000, v4
	s_nop 1
	v_addc_co_u32_e32 v81, vcc, 0, v5, vcc
	global_load_dword v78, v[80:81], off offset:2176 nt
.LBB0_67:
	s_or_b64 exec, exec, s[18:19]
	v_mov_b32_e32 v80, 0
	v_mov_b32_e32 v81, 0
	s_and_saveexec_b64 s[18:19], s[4:5]
	s_cbranch_execz .LBB0_69
	v_add_co_u32_e32 v82, vcc, 0x19e000, v4
	s_nop 1
	v_addc_co_u32_e32 v83, vcc, 0, v5, vcc
	global_load_dword v81, v[82:83], off offset:2304 nt
; template <int MODE  >
; __device__ __forceinline__ void transpose_item(const float* W, int K, int N, bf16_t* WT, int ldt, int koff, const float* ks, float* scr, int item, int lane) {
;     ...
;     for (int i = 0; i < 32; ++i) v[i] = nok ? wp[(size_t)(2 * i) * N] : 0.f;
.LBB0_69:
	s_or_b64 exec, exec, s[18:19]
	s_and_saveexec_b64 s[18:19], s[4:5]
	s_cbranch_execz .LBB0_71
	v_add_co_u32_e32 v82, vcc, 0x1b5000, v4
	s_nop 1
	v_addc_co_u32_e32 v83, vcc, 0, v5, vcc
	global_load_dword v80, v[82:83], off offset:2432 nt
.LBB0_71:
	s_or_b64 exec, exec, s[18:19]
	v_mov_b32_e32 v83, 0
	v_mov_b32_e32 v84, 0
	s_and_saveexec_b64 s[18:19], s[4:5]
	s_cbranch_execz .LBB0_73
	v_add_co_u32_e32 v84, vcc, 0x1cc000, v4
	s_nop 1
	v_addc_co_u32_e32 v85, vcc, 0, v5, vcc
	global_load_dword v84, v[84:85], off offset:2560 nt
.LBB0_73:
	s_or_b64 exec, exec, s[18:19]
	s_and_saveexec_b64 s[18:19], s[4:5]
	s_cbranch_execz .LBB0_75
	v_add_co_u32_e32 v82, vcc, 0x1e3000, v4
	s_nop 1
	v_addc_co_u32_e32 v83, vcc, 0, v5, vcc
	global_load_dword v83, v[82:83], off offset:2688 nt
.LBB0_75:
	s_or_b64 exec, exec, s[18:19]
	v_mov_b32_e32 v85, 0
	v_mov_b32_e32 v86, 0
	s_and_saveexec_b64 s[18:19], s[4:5]
	s_cbranch_execz .LBB0_77
	v_add_co_u32_e32 v86, vcc, 0x1fa000, v4
	s_nop 1
	v_addc_co_u32_e32 v87, vcc, 0, v5, vcc
	global_load_dword v86, v[86:87], off offset:2816 nt
.LBB0_77:
	s_or_b64 exec, exec, s[18:19]
	s_and_saveexec_b64 s[18:19], s[4:5]
	s_cbranch_execz .LBB0_79
	v_add_co_u32_e32 v88, vcc, 0x211000, v4
	s_nop 1
	v_addc_co_u32_e32 v89, vcc, 0, v5, vcc
	global_load_dword v85, v[88:89], off offset:2944 nt
.LBB0_79:
	s_or_b64 exec, exec, s[18:19]
	v_mov_b32_e32 v87, 0
	v_mov_b32_e32 v88, 0
	s_and_saveexec_b64 s[18:19], s[4:5]
	s_cbranch_execz .LBB0_81
	v_add_co_u32_e32 v88, vcc, 0x228000, v4
	s_nop 1
	v_addc_co_u32_e32 v89, vcc, 0, v5, vcc
	global_load_dword v88, v[88:89], off offset:3072 nt
.LBB0_81:
	s_or_b64 exec, exec, s[18:19]
	s_and_saveexec_b64 s[18:19], s[4:5]
	s_cbranch_execz .LBB0_83
	v_add_co_u32_e32 v90, vcc, 0x23f000, v4
	s_nop 1
	v_addc_co_u32_e32 v91, vcc, 0, v5, vcc
	global_load_dword v87, v[90:91], off offset:3200 nt
.LBB0_83:
	s_or_b64 exec, exec, s[18:19]
	v_mov_b32_e32 v90, 0
	v_mov_b32_e32 v91, 0
	s_and_saveexec_b64 s[18:19], s[4:5]
	s_cbranch_execz .LBB0_85
	v_add_co_u32_e32 v92, vcc, 0x256000, v4
	s_nop 1
	v_addc_co_u32_e32 v93, vcc, 0, v5, vcc
	global_load_dword v91, v[92:93], off offset:3328 nt
.LBB0_85:
	s_or_b64 exec, exec, s[18:19]
	s_and_saveexec_b64 s[18:19], s[4:5]
	s_cbranch_execz .LBB0_87
	v_add_co_u32_e32 v92, vcc, 0x26d000, v4
	s_nop 1
	v_addc_co_u32_e32 v93, vcc, 0, v5, vcc
	global_load_dword v90, v[92:93], off offset:3456 nt
.LBB0_87:
	s_or_b64 exec, exec, s[18:19]
	v_mov_b32_e32 v92, 0
	v_mov_b32_e32 v93, 0
	s_and_saveexec_b64 s[18:19], s[4:5]
	s_cbranch_execz .LBB0_89
	v_add_co_u32_e32 v94, vcc, 0x284000, v4
	s_nop 1
	v_addc_co_u32_e32 v95, vcc, 0, v5, vcc
	global_load_dword v93, v[94:95], off offset:3584 nt
.LBB0_89:
	s_or_b64 exec, exec, s[18:19]
	s_and_saveexec_b64 s[18:19], s[4:5]
	s_cbranch_execz .LBB0_91
	v_add_co_u32_e32 v94, vcc, 0x29b000, v4
	s_nop 1
	v_addc_co_u32_e32 v95, vcc, 0, v5, vcc
	global_load_dword v92, v[94:95], off offset:3712 nt
.LBB0_91:
	s_or_b64 exec, exec, s[18:19]
	v_mov_b32_e32 v89, 0
	v_mov_b32_e32 v94, 0
	s_and_saveexec_b64 s[18:19], s[4:5]
	s_cbranch_execz .LBB0_93
	v_add_co_u32_e32 v94, vcc, 0x2b2000, v4
	s_nop 1
	v_addc_co_u32_e32 v95, vcc, 0, v5, vcc
	global_load_dword v94, v[94:95], off offset:3840 nt
.LBB0_93:
	s_or_b64 exec, exec, s[18:19]
	s_and_saveexec_b64 s[18:19], s[4:5]
	s_cbranch_execz .LBB0_95
	v_add_co_u32_e32 v4, vcc, 0x2c9000, v4
	s_nop 1
	v_addc_co_u32_e32 v5, vcc, 0, v5, vcc
	global_load_dword v89, v[4:5], off offset:3968 nt
; __device__ __forceinline__ unsigned cvt_pk_bf16(float lo, float hi) { unsigned r; asm volatile("v_cvt_pk_bf16_f32 %0, %1, %2" : "=v"(r) : "v"(lo), "v"(hi)); return r; }
; #define LDS_WAIT() asm volatile("s_waitcnt lgkmcnt(0)" ::: "memory")
; template <int MODE  >
; __device__ __forceinline__ void transpose_item(const float* W, int K, int N, bf16_t* WT, int ldt, int koff, const float* ks, float* scr, int item, int lane) {
;     ...
;     for (int i = 0; i < 32; ++i) { const int kk = 2 * i + (lane >> 5); float x = v[i]; if (MODE != 0) x *= ks[k0 + kk]; scr[kk * 33 + (lane & 31)] = x; }
;     LDS_WAIT(); asm volatile("" ::: "memory");
;     const int c = lane & 7;
; #pragma unroll
;     for (int j = 0; j < 4; ++j) { const int nl = (lane >> 3) + 8 * j, n = n0 + nl; const float* s = scr + (8 * c) * 33 + nl;
;         u32x4 o; o.x = cvt_pk_bf16(s[0 * 33], s[1 * 33]); o.y = cvt_pk_bf16(s[2 * 33], s[3 * 33]); o.z = cvt_pk_bf16(s[4 * 33], s[5 * 33]); o.w = cvt_pk_bf16(s[6 * 33], s[7 * 33]);
;         int dst = n; if (MODE == 1) dst = n < 7680 ? n : (n < 7696 ? ZAG + (n - 7680) : n - 16);
;         if (n < N) *(u32x4*)(WT + (size_t)dst * ldt + koff + k0 + 8 * c) = o; }
.LBB0_95:
	s_or_b64 exec, exec, s[18:19]
	v_sub_u32_e32 v4, 0, v3
	v_ashrrev_i32_e32 v3, 31, v2
	v_lshl_add_u64 v[2:3], v[2:3], 2, s[74:75]
	global_load_dword v2, v[2:3], off nt
	v_add_u32_e32 v82, v63, v4
	v_sub_u32_e32 v5, v64, v8
	v_lshlrev_b32_e32 v8, 5, v5
	s_waitcnt vmcnt(0)
	v_mul_f32_e32 v2, v23, v2
	v_ashrrev_i32_e32 v23, 31, v22
	ds_write_b32 v26, v2
	v_lshl_add_u64 v[2:3], v[22:23], 0, v[6:7]
	v_lshl_add_u64 v[2:3], v[2:3], 2, s[74:75]
	global_load_dword v4, v[2:3], off offset:8 nt
	s_waitcnt vmcnt(0)
	v_mul_f32_e32 v4, v24, v4
	ds_write_b32 v32, v4
	global_load_dword v4, v[2:3], off offset:16 nt
	v_or_b32_e32 v24, v8, v27
	s_waitcnt vmcnt(0)
	v_mul_f32_e32 v4, v65, v4
	ds_write_b32 v33, v4
	global_load_dword v4, v[2:3], off offset:24 nt
	v_add_u32_e32 v65, v82, v27
	v_cmp_lt_i32_e32 vcc, s34, v65
	s_waitcnt vmcnt(0)
	v_mul_f32_e32 v4, v25, v4
	ds_write_b32 v34, v4
	global_load_dword v4, v[2:3], off offset:32 nt
	s_waitcnt vmcnt(0)
	v_mul_f32_e32 v4, v67, v4
	ds_write_b32 v35, v4
	global_load_dword v4, v[2:3], off offset:40 nt
	s_waitcnt vmcnt(0)
	v_mul_f32_e32 v4, v66, v4
	ds_write_b32 v36, v4
	global_load_dword v4, v[2:3], off offset:48 nt
	s_waitcnt vmcnt(0)
	v_mul_f32_e32 v4, v69, v4
	ds_write_b32 v37, v4
	global_load_dword v4, v[2:3], off offset:56 nt
	s_waitcnt vmcnt(0)
	v_mul_f32_e32 v4, v68, v4
	ds_write_b32 v38, v4
	global_load_dword v4, v[2:3], off offset:64 nt
	s_waitcnt vmcnt(0)
	v_mul_f32_e32 v4, v71, v4
	ds_write_b32 v39, v4
	global_load_dword v4, v[2:3], off offset:72 nt
	s_waitcnt vmcnt(0)
	v_mul_f32_e32 v4, v70, v4
	ds_write_b32 v40, v4
	global_load_dword v4, v[2:3], off offset:80 nt
	s_waitcnt vmcnt(0)
	v_mul_f32_e32 v4, v73, v4
	ds_write_b32 v41, v4
	global_load_dword v4, v[2:3], off offset:88 nt
	s_waitcnt vmcnt(0)
	v_mul_f32_e32 v4, v72, v4
	ds_write_b32 v42, v4
	global_load_dword v4, v[2:3], off offset:96 nt
	s_waitcnt vmcnt(0)
	v_mul_f32_e32 v4, v75, v4
	ds_write_b32 v43, v4
	global_load_dword v4, v[2:3], off offset:104 nt
	s_waitcnt vmcnt(0)
	v_mul_f32_e32 v4, v74, v4
	ds_write_b32 v44, v4
	global_load_dword v4, v[2:3], off offset:112 nt
	s_waitcnt vmcnt(0)
	v_mul_f32_e32 v4, v77, v4
	ds_write_b32 v45, v4
	global_load_dword v4, v[2:3], off offset:120 nt
	s_waitcnt vmcnt(0)
	v_mul_f32_e32 v4, v76, v4
	ds_write_b32 v46, v4
	global_load_dword v4, v[2:3], off offset:128 nt
	s_waitcnt vmcnt(0)
	v_mul_f32_e32 v4, v79, v4
	ds_write_b32 v47, v4
	global_load_dword v4, v[2:3], off offset:136 nt
	s_waitcnt vmcnt(0)
	v_mul_f32_e32 v4, v78, v4
	ds_write_b32 v48, v4
	global_load_dword v4, v[2:3], off offset:144 nt
	s_waitcnt vmcnt(0)
	v_mul_f32_e32 v4, v81, v4
	ds_write_b32 v49, v4
	global_load_dword v4, v[2:3], off offset:152 nt
	s_waitcnt vmcnt(0)
	v_mul_f32_e32 v4, v80, v4
	ds_write_b32 v50, v4
	global_load_dword v4, v[2:3], off offset:160 nt
	s_waitcnt vmcnt(0)
	v_mul_f32_e32 v4, v84, v4
	ds_write_b32 v51, v4
	global_load_dword v4, v[2:3], off offset:168 nt
	s_waitcnt vmcnt(0)
	v_mul_f32_e32 v4, v83, v4
	ds_write_b32 v52, v4
	global_load_dword v4, v[2:3], off offset:176 nt
	s_waitcnt vmcnt(0)
	v_mul_f32_e32 v4, v86, v4
	ds_write_b32 v53, v4
	global_load_dword v4, v[2:3], off offset:184 nt
	s_waitcnt vmcnt(0)
	v_mul_f32_e32 v4, v85, v4
	ds_write_b32 v54, v4
	global_load_dword v4, v[2:3], off offset:192 nt
	s_waitcnt vmcnt(0)
	v_mul_f32_e32 v4, v88, v4
	ds_write_b32 v55, v4
	global_load_dword v4, v[2:3], off offset:200 nt
	s_waitcnt vmcnt(0)
	v_mul_f32_e32 v4, v87, v4
	ds_write_b32 v56, v4
	global_load_dword v4, v[2:3], off offset:208 nt
	s_waitcnt vmcnt(0)
	v_mul_f32_e32 v4, v91, v4
	ds_write_b32 v57, v4
	global_load_dword v4, v[2:3], off offset:216 nt
	s_waitcnt vmcnt(0)
	v_mul_f32_e32 v4, v90, v4
	ds_write_b32 v58, v4
	global_load_dword v4, v[2:3], off offset:224 nt
	s_waitcnt vmcnt(0)
	v_mul_f32_e32 v4, v93, v4
	ds_write_b32 v59, v4
	global_load_dword v4, v[2:3], off offset:232 nt
	s_waitcnt vmcnt(0)
	v_mul_f32_e32 v4, v92, v4
	ds_write_b32 v60, v4
	global_load_dword v4, v[2:3], off offset:240 nt
	s_waitcnt vmcnt(0)
	v_mul_f32_e32 v4, v94, v4
	global_load_dword v2, v[2:3], off offset:248 nt
	ds_write_b32 v61, v4
	s_waitcnt vmcnt(0)
	v_mul_f32_e32 v2, v89, v2
	ds_write_b32 v62, v2
	s_waitcnt lgkmcnt(0)
	ds_read2_b32 v[2:3], v28 offset1:33
	s_waitcnt lgkmcnt(0)
	v_cvt_pk_bf16_f32 v2, v2, v3
	ds_read2_b32 v[4:5], v28 offset0:66 offset1:99
	s_waitcnt lgkmcnt(0)
	v_cvt_pk_bf16_f32 v3, v4, v5
	ds_read2_b32 v[4:5], v28 offset0:132 offset1:165
	s_waitcnt lgkmcnt(0)
	v_cvt_pk_bf16_f32 v4, v4, v5
	ds_read2_b32 v[66:67], v28 offset0:198 offset1:231
	s_waitcnt lgkmcnt(0)
	v_cvt_pk_bf16_f32 v5, v66, v67
	s_and_saveexec_b64 s[4:5], vcc
	s_cbranch_execz .LBB0_101
	v_cmp_lt_u32_e32 vcc, s35, v82
	s_and_saveexec_b64 s[18:19], vcc
	s_xor_b64 s[18:19], exec, s[18:19]
	v_add_u32_e32 v24, -16, v24
	s_andn2_saveexec_b64 s[18:19], s[18:19]
	v_add_u32_e32 v24, 0x1000, v65
	s_or_b64 exec, exec, s[18:19]

; __device__ __forceinline__ unsigned cvt_pk_bf16(float lo, float hi) { unsigned r; asm volatile("v_cvt_pk_bf16_f32 %0, %1, %2" : "=v"(r) : "v"(lo), "v"(hi)); return r; }
; __device__ __forceinline__ void phase0(const Args& a, unsigned char* lds, int tid) {
;     ...
;     for (int m = gw; m < M; m += NGW) {
;         const float* xr = m < MP ? a.xp + (size_t)m * DM : a.xs + (size_t)(m - MP) * DM;
;         f32x4 v[8]; float s = 0.f;
; #pragma unroll
;         for (int j = 0; j < 8; ++j) { v[j] = ((const f32x4*)xr)[lane + 64 * j]; s += (v[j][0] * v[j][0] + v[j][1] * v[j][1]) + (v[j][2] * v[j][2] + v[j][3] * v[j][3]); }
;         s = wave_sum(s); const float rs1 = rsqrtf(s * (1.0f / DM) + EPS);
;         u32x2* o = (u32x2*)(XB + (size_t)m * DM);
; #pragma unroll
;         for (int j = 0; j < 8; ++j) { u32x2 w; w.x = cvt_pk_bf16(v[j][0] * rs1, v[j][1] * rs1); w.y = cvt_pk_bf16(v[j][2] * rs1, v[j][3] * rs1); o[lane + 64 * j] = w; }
;     }
.LBB0_125:
	s_or_b64 exec, exec, s[16:17]
	v_lshl_add_u64 v[46:47], v[22:23], 0, v[8:9]
	global_load_dwordx4 v[30:33], v[46:47], off nt
	global_load_dwordx4 v[34:37], v[46:47], off offset:1024 nt
	global_load_dwordx4 v[38:41], v[46:47], off offset:2048 nt
	v_lshl_add_u64 v[42:43], v[22:23], 0, v[10:11]
	global_load_dwordx4 v[42:45], v[42:43], off nt
	s_nop 0
	global_load_dwordx4 v[46:49], v[46:47], off offset:3072 nt
	v_lshl_add_u64 v[50:51], v[22:23], 0, v[12:13]
	global_load_dwordx4 v[50:53], v[50:51], off nt
	v_lshl_add_u64 v[54:55], v[22:23], 0, v[16:17]
	v_lshl_add_u64 v[22:23], v[22:23], 0, v[14:15]
	global_load_dwordx4 v[58:61], v[22:23], off nt
	v_lshlrev_b64 v[20:21], 12, v[20:21]
	global_load_dwordx4 v[54:57], v[54:55], off nt
	v_lshl_add_u64 v[20:21], v[4:5], 0, v[20:21]
	v_lshl_add_u64 v[18:19], v[18:19], 0, s[88:89]
	v_lshl_add_u64 v[6:7], v[6:7], 0, s[4:5]
	s_waitcnt vmcnt(7)
	v_mov_b32_e32 v62, v31
	s_waitcnt vmcnt(6)
	v_mov_b32_e32 v63, v35
	v_mov_b32_e32 v66, v33
	v_mov_b32_e32 v67, v37
	v_mov_b32_e32 v22, v30
	v_mov_b32_e32 v23, v34
	v_mov_b32_e32 v64, v32
	v_mov_b32_e32 v65, v36
	s_waitcnt vmcnt(5)
	v_pk_mul_f32 v[68:69], v[40:41], v[40:41]
	v_pk_mul_f32 v[70:71], v[38:39], v[38:39]
	v_pk_mul_f32 v[62:63], v[62:63], v[62:63]
	v_pk_mul_f32 v[66:67], v[66:67], v[66:67]
	v_pk_mov_b32 v[82:83], v[70:71], v[68:69] op_sel:[1,0]
	v_mov_b32_e32 v71, v69
	v_pk_fma_f32 v[22:23], v[22:23], v[22:23], v[62:63]
	v_pk_fma_f32 v[62:63], v[64:65], v[64:65], v[66:67]
	s_waitcnt vmcnt(3)
	v_mul_f32_e32 v2, v47, v47
	v_mul_f32_e32 v72, v49, v49
	v_pk_add_f32 v[64:65], v[82:83], v[70:71]
	v_pk_add_f32 v[22:23], v[22:23], v[62:63]
	v_mul_f32_e32 v81, v42, v42
	v_mul_f32_e32 v86, v43, v43
	v_mul_f32_e32 v87, v44, v44
	v_mul_f32_e32 v88, v45, v45
	v_pk_fma_f32 v[68:69], v[46:47], v[46:47], v[2:3] op_sel_hi:[1,1,0]
	v_pk_fma_f32 v[72:73], v[48:49], v[48:49], v[72:73] op_sel_hi:[1,1,0]
	v_pk_add_f32 v[62:63], v[64:65], v[64:65] op_sel:[0,1] op_sel_hi:[1,0]
	v_pk_add_f32 v[22:23], v[22:23], v[22:23] op_sel:[0,1] op_sel_hi:[1,0]
	s_waitcnt vmcnt(2)
	v_pk_mul_f32 v[74:75], v[52:53], v[52:53]
	v_pk_mul_f32 v[76:77], v[50:51], v[50:51]
	v_mov_b32_e32 v69, v87
	v_mov_b32_e32 v73, v88
	v_mov_b32_e32 v63, v86
	v_mov_b32_e32 v23, v81
	v_pk_mov_b32 v[84:85], v[76:77], v[74:75] op_sel:[1,0]
	v_mov_b32_e32 v77, v75
	v_pk_add_f32 v[64:65], v[68:69], v[72:73]
	v_pk_add_f32 v[22:23], v[22:23], v[62:63]
	s_waitcnt vmcnt(1)
	v_mul_f32_e32 v78, v59, v59
	v_mul_f32_e32 v80, v61, v61
	v_pk_add_f32 v[66:67], v[84:85], v[76:77]
	v_pk_add_f32 v[22:23], v[22:23], v[64:65]
	s_waitcnt vmcnt(0)
	v_mul_f32_e32 v89, v54, v54
	v_mul_f32_e32 v90, v55, v55
	v_mul_f32_e32 v91, v56, v56
	v_mul_f32_e32 v92, v57, v57
	v_pk_fma_f32 v[74:75], v[58:59], v[58:59], v[78:79] op_sel_hi:[1,1,0]
	v_pk_fma_f32 v[78:79], v[60:61], v[60:61], v[80:81] op_sel_hi:[1,1,0]
	v_pk_add_f32 v[66:67], v[66:67], v[66:67] op_sel:[0,1] op_sel_hi:[1,0]
	v_pk_add_f32 v[22:23], v[22:23], v[22:23] op_sel:[0,1] op_sel_hi:[1,0]
	v_mov_b32_e32 v75, v91
	v_mov_b32_e32 v79, v92
	v_mov_b32_e32 v67, v90
	v_mov_b32_e32 v23, v89
	v_pk_add_f32 v[68:69], v[74:75], v[78:79]
	v_pk_add_f32 v[22:23], v[22:23], v[66:67]
	s_nop 0
	v_pk_add_f32 v[22:23], v[22:23], v[68:69]
	s_nop 0
	v_add_f32_e32 v2, v22, v23
	ds_bpermute_b32 v22, v1, v2
	s_waitcnt lgkmcnt(0)
	v_add_f32_e32 v2, v2, v22
	ds_bpermute_b32 v22, v24, v2
	s_waitcnt lgkmcnt(0)
	v_add_f32_e32 v2, v2, v22
	ds_bpermute_b32 v22, v25, v2
	s_waitcnt lgkmcnt(0)
	v_add_f32_e32 v2, v2, v22
	ds_bpermute_b32 v22, v26, v2
	s_waitcnt lgkmcnt(0)
	v_add_f32_e32 v2, v2, v22
	ds_bpermute_b32 v22, v27, v2
	s_waitcnt lgkmcnt(0)
	v_add_f32_e32 v2, v2, v22
	ds_bpermute_b32 v22, v28, v2
	s_waitcnt lgkmcnt(0)
	v_add_f32_e32 v2, v2, v22
	v_fmamk_f32 v2, v2, 0x3a000000, v29
	v_mul_f32_e32 v22, 0x4b800000, v2
	v_cmp_gt_f32_e32 vcc, s18, v2
	s_nop 1
	v_cndmask_b32_e32 v2, v2, v22, vcc
	v_rsq_f32_e32 v2, v2
	s_nop 0
	v_mul_f32_e32 v22, 0x45800000, v2
	v_cndmask_b32_e32 v2, v2, v22, vcc
	v_mul_f32_e32 v22, v30, v2
	v_mul_f32_e32 v23, v31, v2
	v_mul_f32_e32 v30, v32, v2
	v_mul_f32_e32 v31, v33, v2
	v_cvt_pk_bf16_f32 v22, v22, v23
	v_cvt_pk_bf16_f32 v23, v30, v31
	v_mul_f32_e32 v32, v34, v2
	v_mul_f32_e32 v33, v35, v2
	v_mul_f32_e32 v34, v36, v2
	v_mul_f32_e32 v35, v37, v2
	global_store_dwordx2 v[20:21], v[22:23], off
	v_cvt_pk_bf16_f32 v22, v32, v33
	v_cvt_pk_bf16_f32 v23, v34, v35
	v_mul_f32_e32 v36, v38, v2
	v_mul_f32_e32 v37, v39, v2
	v_mul_f32_e32 v38, v40, v2
	v_mul_f32_e32 v39, v41, v2
	global_store_dwordx2 v[20:21], v[22:23], off offset:512
	v_cvt_pk_bf16_f32 v22, v36, v37
	v_cvt_pk_bf16_f32 v23, v38, v39
	v_mul_f32_e32 v40, v46, v2
	v_mul_f32_e32 v41, v47, v2
	v_mul_f32_e32 v46, v48, v2
	v_mul_f32_e32 v47, v49, v2
	global_store_dwordx2 v[20:21], v[22:23], off offset:1024
	v_cvt_pk_bf16_f32 v22, v40, v41
	v_cvt_pk_bf16_f32 v23, v46, v47
	v_mul_f32_e32 v42, v42, v2
	v_mul_f32_e32 v43, v43, v2
	v_mul_f32_e32 v44, v44, v2
	v_mul_f32_e32 v45, v45, v2
	global_store_dwordx2 v[20:21], v[22:23], off offset:1536
	v_cvt_pk_bf16_f32 v22, v42, v43
	v_cvt_pk_bf16_f32 v23, v44, v45
	v_mul_f32_e32 v48, v50, v2
	v_mul_f32_e32 v49, v51, v2
	v_mul_f32_e32 v50, v52, v2
	v_mul_f32_e32 v51, v53, v2
	global_store_dwordx2 v[20:21], v[22:23], off offset:2048
	v_cvt_pk_bf16_f32 v22, v48, v49
	v_cvt_pk_bf16_f32 v23, v50, v51
	v_cmp_lt_i32_e32 vcc, s19, v18
	v_mul_f32_e32 v52, v58, v2
	v_mul_f32_e32 v53, v59, v2
	v_mul_f32_e32 v58, v60, v2
	v_mul_f32_e32 v59, v61, v2
	global_store_dwordx2 v[20:21], v[22:23], off offset:2560
	v_cvt_pk_bf16_f32 v22, v52, v53
	v_cvt_pk_bf16_f32 v23, v58, v59
	s_or_b64 s[6:7], vcc, s[6:7]
	v_mul_f32_e32 v54, v54, v2
	v_mul_f32_e32 v55, v55, v2
	v_mul_f32_e32 v56, v56, v2
	v_mul_f32_e32 v2, v57, v2
	global_store_dwordx2 v[20:21], v[22:23], off offset:3072
	v_cvt_pk_bf16_f32 v22, v54, v55
	v_cvt_pk_bf16_f32 v23, v56, v2
	global_store_dwordx2 v[20:21], v[22:23], off offset:3584
	s_andn2_b64 exec, exec, s[6:7]
	s_cbranch_execz .LBB0_128

; __device__ __forceinline__ void unpack8(const u32x4& w, float (&f)[8]) { f[0] = bflo(w.x); f[1] = bfhi(w.x); f[2] = bflo(w.y); f[3] = bfhi(w.y); f[4] = bflo(w.z); f[5] = bfhi(w.z); f[6] = bflo(w.w); f[7] = bfhi(w.w); }
; __global__ void __launch_bounds__(512, 2) hybrid_fwd(Args a) {
;     ...
;         for (int m = gw; m < M; m += NGW) { const float sf_ = wave_sum(lane < 32 ? SSF[(size_t)m * 32 + lane] : 0.f); const float rs = rsqrtf(sf_ * (1.0f / DM) + EPS);
;             const u32x4* xb = (const u32x4*)(Y + (size_t)m * DM); f32x4* yr = (f32x4*)(a.out + (size_t)m * DM); u32x4 xw[4];
; #pragma unroll
;             for (int j = 0; j < 4; ++j) xw[j] = xb[lane + 64 * j];
; #pragma unroll
;             for (int j = 0; j < 4; ++j) { float f[8]; pg8::unpack8(xw[j], f); const int c = (lane + 64 * j) * 8; const f32x4 w0 = *(const f32x4*)(a.fnorm + c), w1 = *(const f32x4*)(a.fnorm + c + 4);
;                 yr[(lane + 64 * j) * 2] = (f32x4){f[0] * rs * w0[0], f[1] * rs * w0[1], f[2] * rs * w0[2], f[3] * rs * w0[3]}; yr[(lane + 64 * j) * 2 + 1] = (f32x4){f[4] * rs * w1[0], f[5] * rs * w1[1], f[6] * rs * w1[2], f[7] * rs * w1[3]}; } }
.LBB0_1107:
	s_or_b64 exec, exec, s[0:1]
	v_lshl_add_u64 v[22:23], s[86:87], 0, v[8:9]
	v_add_co_u32_e64 v46, s[0:1], s11, v22
	s_waitcnt vmcnt(0)
	ds_bpermute_b32 v34, v14, v21
	v_addc_co_u32_e64 v47, s[0:1], 0, v23, s[0:1]
	global_load_dwordx4 v[22:25], v[46:47], off
	global_load_dwordx4 v[26:29], v[0:1], off
	global_load_dwordx4 v[30:33], v[0:1], off offset:16
	v_add_u32_e32 v184, s88, v184
	s_waitcnt lgkmcnt(0)
	v_add_f32_e32 v21, v21, v34
	ds_bpermute_b32 v34, v15, v21
	v_lshl_add_u64 v[8:9], v[8:9], 0, s[2:3]
	v_lshl_add_u64 v[12:13], v[12:13], 0, s[6:7]
	s_waitcnt lgkmcnt(0)
	v_add_f32_e32 v21, v21, v34
	ds_bpermute_b32 v34, v16, v21
	s_waitcnt lgkmcnt(0)
	v_add_f32_e32 v21, v21, v34
	ds_bpermute_b32 v34, v17, v21
	s_waitcnt lgkmcnt(0)
	v_add_f32_e32 v21, v21, v34
	ds_bpermute_b32 v34, v18, v21
	s_waitcnt lgkmcnt(0)
	v_add_f32_e32 v21, v21, v34
	ds_bpermute_b32 v34, v19, v21
	s_waitcnt lgkmcnt(0)
	v_add_f32_e32 v21, v21, v34
	v_fmamk_f32 v21, v21, 0x3a000000, v20
	v_mul_f32_e32 v34, 0x4b800000, v21
	v_cmp_gt_f32_e64 s[0:1], s10, v21
	s_waitcnt vmcnt(2)
	v_lshlrev_b32_e32 v48, 16, v22
	v_cndmask_b32_e64 v21, v21, v34, s[0:1]
	v_rsq_f32_e32 v21, v21
	global_load_dwordx4 v[34:37], v[46:47], off offset:1024
	global_load_dwordx4 v[38:41], v[46:47], off offset:2048
	global_load_dwordx4 v[42:45], v[46:47], off offset:3072
	v_and_b32_e32 v49, 0xffff0000, v22
	v_lshlrev_b32_e32 v22, 16, v23
	v_mul_f32_e32 v46, 0x45800000, v21
	v_cndmask_b32_e64 v46, v21, v46, s[0:1]
	v_and_b32_e32 v23, 0xffff0000, v23
	v_lshlrev_b32_e32 v50, 16, v24
	v_and_b32_e32 v51, 0xffff0000, v24
	v_lshlrev_b32_e32 v24, 16, v25
	v_and_b32_e32 v25, 0xffff0000, v25
	v_pk_mul_f32 v[48:49], v[46:47], v[48:49] op_sel_hi:[0,1]
	v_pk_mul_f32 v[52:53], v[46:47], v[22:23] op_sel_hi:[0,1]
	v_pk_mul_f32 v[50:51], v[46:47], v[50:51] op_sel_hi:[0,1]
	v_pk_mul_f32 v[54:55], v[46:47], v[24:25] op_sel_hi:[0,1]
	s_waitcnt vmcnt(4)
	v_pk_mul_f32 v[22:23], v[26:27], v[48:49]
	v_pk_mul_f32 v[24:25], v[28:29], v[52:53]
	s_waitcnt vmcnt(3)
	v_pk_mul_f32 v[26:27], v[30:31], v[50:51]
	v_pk_mul_f32 v[28:29], v[32:33], v[54:55]
	global_store_dwordx4 v[10:11], v[22:25], off offset:-4096 nt
	global_store_dwordx4 v[10:11], v[26:29], off offset:-4080 nt
	global_load_dwordx4 v[22:25], v[2:3], off
	s_nop 0
	global_load_dwordx4 v[26:29], v[2:3], off offset:16
	v_cmp_lt_i32_e64 s[0:1], s12, v184
	s_or_b64 s[8:9], s[0:1], s[8:9]
	s_waitcnt vmcnt(6)
	v_lshlrev_b32_e32 v30, 16, v34
	v_and_b32_e32 v31, 0xffff0000, v34
	v_lshlrev_b32_e32 v32, 16, v35
	v_and_b32_e32 v33, 0xffff0000, v35
	v_lshlrev_b32_e32 v34, 16, v36
	v_and_b32_e32 v35, 0xffff0000, v36
	v_lshlrev_b32_e32 v36, 16, v37
	v_and_b32_e32 v37, 0xffff0000, v37
	v_pk_mul_f32 v[30:31], v[46:47], v[30:31] op_sel_hi:[0,1]
	v_pk_mul_f32 v[32:33], v[46:47], v[32:33] op_sel_hi:[0,1]
	v_pk_mul_f32 v[34:35], v[46:47], v[34:35] op_sel_hi:[0,1]
	v_pk_mul_f32 v[36:37], v[46:47], v[36:37] op_sel_hi:[0,1]
	s_waitcnt vmcnt(1)
	v_pk_mul_f32 v[22:23], v[22:23], v[30:31]
	v_pk_mul_f32 v[24:25], v[24:25], v[32:33]
	s_waitcnt vmcnt(0)
	v_pk_mul_f32 v[26:27], v[26:27], v[34:35]
	v_pk_mul_f32 v[28:29], v[28:29], v[36:37]
	global_store_dwordx4 v[10:11], v[22:25], off offset:-2048 nt
	global_store_dwordx4 v[10:11], v[26:29], off offset:-2032 nt
	global_load_dwordx4 v[22:25], v[4:5], off
	s_nop 0
	global_load_dwordx4 v[26:29], v[4:5], off offset:16
	v_lshlrev_b32_e32 v30, 16, v38
	v_and_b32_e32 v31, 0xffff0000, v38
	v_lshlrev_b32_e32 v32, 16, v39
	v_and_b32_e32 v33, 0xffff0000, v39
	v_lshlrev_b32_e32 v34, 16, v40
	v_and_b32_e32 v35, 0xffff0000, v40
	v_lshlrev_b32_e32 v36, 16, v41
	v_and_b32_e32 v37, 0xffff0000, v41
	v_pk_mul_f32 v[30:31], v[46:47], v[30:31] op_sel_hi:[0,1]
	v_pk_mul_f32 v[32:33], v[46:47], v[32:33] op_sel_hi:[0,1]
	v_pk_mul_f32 v[34:35], v[46:47], v[34:35] op_sel_hi:[0,1]
	v_pk_mul_f32 v[36:37], v[46:47], v[36:37] op_sel_hi:[0,1]
	s_waitcnt vmcnt(1)
	v_pk_mul_f32 v[22:23], v[22:23], v[30:31]
	v_pk_mul_f32 v[24:25], v[24:25], v[32:33]
	s_waitcnt vmcnt(0)
	v_pk_mul_f32 v[26:27], v[26:27], v[34:35]
	v_pk_mul_f32 v[28:29], v[28:29], v[36:37]
	global_store_dwordx4 v[10:11], v[22:25], off nt
	global_store_dwordx4 v[10:11], v[26:29], off offset:16 nt
	global_load_dwordx4 v[22:25], v[6:7], off
	s_nop 0
	global_load_dwordx4 v[26:29], v[6:7], off offset:16
	v_lshlrev_b32_e32 v30, 16, v42
	v_and_b32_e32 v31, 0xffff0000, v42
	v_lshlrev_b32_e32 v32, 16, v43
	v_and_b32_e32 v33, 0xffff0000, v43
	v_lshlrev_b32_e32 v34, 16, v44
	v_and_b32_e32 v35, 0xffff0000, v44
	v_lshlrev_b32_e32 v36, 16, v45
	v_and_b32_e32 v37, 0xffff0000, v45
	v_pk_mul_f32 v[30:31], v[46:47], v[30:31] op_sel_hi:[0,1]
	v_pk_mul_f32 v[32:33], v[46:47], v[32:33] op_sel_hi:[0,1]
	v_pk_mul_f32 v[34:35], v[46:47], v[34:35] op_sel_hi:[0,1]
	v_pk_mul_f32 v[36:37], v[46:47], v[36:37] op_sel_hi:[0,1]
	s_waitcnt vmcnt(1)
	v_pk_mul_f32 v[22:23], v[22:23], v[30:31]
	v_pk_mul_f32 v[24:25], v[24:25], v[32:33]
	s_waitcnt vmcnt(0)
	v_pk_mul_f32 v[26:27], v[26:27], v[34:35]
	v_pk_mul_f32 v[28:29], v[28:29], v[36:37]
	global_store_dwordx4 v[10:11], v[22:25], off offset:2048 nt
	global_store_dwordx4 v[10:11], v[26:29], off offset:2064 nt
	v_lshl_add_u64 v[10:11], v[10:11], 0, s[4:5]
	s_andn2_b64 exec, exec, s[8:9]
	s_cbranch_execz .LBB0_1110
